# mixer projections H placed class-locally inside the ACT region (per-XCD 4 MiB shift) so every in-loop grid barrier can be XCD-local
# speedup vs baseline: 1.0093x; 1.0043x over previous
.LBB0_469:
	s_or_b64 exec, exec, s[0:1]
	v_readlane_b32 s12, v254, 0
	v_readlane_b32 s14, v254, 2
	v_readlane_b32 s15, v254, 3
	s_add_u32 s84, s14, 0x5400000
	s_addc_u32 s85, s15, 0
	s_add_u32 s66, s14, 0x9400000
	s_addc_u32 s67, s15, 0
	s_add_u32 s68, s14, 0x14400000
	s_addc_u32 s69, s15, 0
	s_add_u32 s0, s14, 0x18400000
	s_addc_u32 s1, s15, 0
	v_readlane_b32 s13, v254, 1
	v_writelane_b32 v254, s0, 12
	v_lshl_add_u64 v[0:1], v[0:1], 2, s[10:11]
	s_movk_i32 s79, 0x161
	v_writelane_b32 v254, s1, 13
	s_add_u32 s0, s14, 0x10200
	s_addc_u32 s1, s15, 0
	v_writelane_b32 v254, s0, 14
	s_movk_i32 s3, 0x91
	v_mbcnt_hi_u32_b32 v241, -1, v57
	v_writelane_b32 v254, s1, 15
	s_mov_b64 s[0:1], 0x1400
	v_lshl_add_u64 v[178:179], v[0:1], 0, s[0:1]
	s_mov_b64 s[0:1], 0x2400
	v_lshl_add_u64 v[176:177], v[0:1], 0, s[0:1]
	s_add_u32 s0, s14, 0x13400
	s_addc_u32 s1, s15, 0
	v_writelane_b32 v254, s0, 16
	v_and_b32_e32 v0, 64, v241
	s_mov_b32 s71, 1
	v_writelane_b32 v254, s1, 17
	s_add_u32 s0, s14, 0x13500
	s_addc_u32 s1, s15, 0
	s_add_u32 s58, s14, 0x400000
	s_addc_u32 s61, s15, 0
	s_ashr_i32 s70, s56, 31
	s_ashr_i32 s75, s74, 31
	v_writelane_b32 v254, s0, 18
	s_cmpk_lt_i32 s74, 0xb00
	v_mov_b32_e32 v1, 0
	v_writelane_b32 v254, s1, 19
	s_cselect_b64 s[0:1], -1, 0
	v_writelane_b32 v254, s0, 20
	v_mov_b32_e32 v244, 1
	v_mov_b32_e32 v245, 0x358637bd
	v_writelane_b32 v254, s1, 21
	s_lshr_b32 s0, s75, 29
	s_add_i32 s0, s74, s0
	s_ashr_i32 s4, s0, 3
	s_and_b32 s0, s0, -8
	s_sub_i32 s5, s74, s0
	s_cmpk_lt_i32 s74, 0x480
	s_cselect_b64 s[0:1], -1, 0
	s_add_u32 s72, s14, 0x100000
	v_writelane_b32 v254, s0, 22
	s_addc_u32 s73, s15, 0
	s_mov_b32 s12, 0xf800000
	v_writelane_b32 v254, s1, 23
	s_add_u32 s0, s14, 0x300000
	v_writelane_b32 v254, s0, 24
	s_addc_u32 s0, s15, 0
	s_cmpk_lt_i32 s74, 0x200
	v_writelane_b32 v254, s0, 25
	s_cselect_b64 s[0:1], -1, 0
	s_lshl_b32 s2, s5, 6
	v_writelane_b32 v254, s0, 26
	s_cmpk_lt_i32 s74, 0xa00
	v_mov_b32_e32 v246, 0x260
	v_writelane_b32 v254, s1, 27
	s_cselect_b64 s[0:1], -1, 0
	v_writelane_b32 v254, s0, 28
	s_movk_i32 s81, 0x4000
	s_movk_i32 s76, 0x1200
	v_writelane_b32 v254, s1, 29
	s_and_b64 s[0:1], s[62:63], exec
	s_cselect_b32 s77, 4, 1
	s_add_u32 s0, s14, 0x380000
	v_writelane_b32 v254, s0, 30
	s_addc_u32 s0, s15, 0
	v_writelane_b32 v254, s0, 31
	s_and_b64 s[0:1], s[62:63], exec
	s_cselect_b32 s80, 2, 1
	s_cmp_lt_i32 s5, 0
	s_cselect_b32 s1, s79, 0x160
	s_mul_i32 s0, s5, 0x41
	s_mul_i32 s1, s5, s1
	s_cselect_b32 s6, s3, 0x90
	s_cselect_b32 s7, s0, s2
	s_add_i32 s1, s1, s4
	s_mul_hi_i32 s0, s1, 0x2e8ba2e9
	s_lshr_b32 s2, s0, 31
	s_ashr_i32 s0, s0, 5
	s_add_i32 s0, s0, s2
	s_mul_i32 s2, s0, 0xb0
	s_sub_i32 s1, s1, s2
	s_lshl_b32 s3, s0, 3
	s_bfe_u32 s0, s1, 0x3001c
	s_add_i32 s2, s1, s0
	s_sext_i32_i16 s8, s2
	s_and_b32 s2, s2, 0xfff8
	s_sub_i32 s1, s1, s2
	s_sext_i32_i16 s1, s1
	s_add_i32 s10, s3, s1
	s_ashr_i32 s1, s8, 3
	s_lshr_b32 s0, s8, 3
	v_writelane_b32 v254, s1, 32
	s_mov_b32 s2, s10
	v_writelane_b32 v254, s2, 33
	s_bfe_i64 s[0:1], s[0:1], 0x100000
	s_ashr_i32 s11, s10, 31
	v_writelane_b32 v254, s3, 34
	s_lshl_b64 s[0:1], s[0:1], 19
	s_lshl_b64 s[2:3], s[10:11], 19
	v_writelane_b32 v254, s0, 35
	v_mov_b32_e32 v247, 0x3727c5ac
	v_xor_b32_e32 v243, 1, v241
	v_writelane_b32 v254, s1, 36
	s_add_u32 s0, s84, s2
	s_addc_u32 s1, s85, s3
	s_add_u32 s2, s0, 0x40000
	v_writelane_b32 v254, s0, 37
	s_addc_u32 s3, s1, 0
	v_add_u32_e32 v242, 64, v0
	v_writelane_b32 v254, s1, 38
	s_mul_i32 s0, s5, s6
	s_add_i32 s0, s0, s4
	v_writelane_b32 v254, s2, 39
	s_mul_hi_i32 s1, s0, 0x38e38e39
	v_mov_b32_e32 v248, 0x1200
	v_writelane_b32 v254, s3, 40
	s_lshr_b32 s2, s1, 31
	s_ashr_i32 s1, s1, 4
	s_add_i32 s1, s1, s2
	s_mul_i32 s2, s1, 0x48
	s_sub_i32 s2, s0, s2
	s_bfe_i32 s0, s2, 0x80000
	s_bfe_u32 s0, s0, 0x3000c
	s_add_i32 s3, s2, s0
	s_bfe_i32 s0, s3, 0x80000
	s_and_b32 s3, s3, 0xf8
	s_sub_i32 s2, s2, s3
	s_lshl_b32 s1, s1, 3
	s_sext_i32_i16 s5, s0
	s_sext_i32_i8 s2, s2
	s_add_i32 s6, s1, s2
	s_ashr_i32 s1, s5, 3
	v_writelane_b32 v254, s1, 41
	s_add_i32 s1, s7, s4
	s_ashr_i32 s2, s1, 31
	s_lshr_b32 s2, s2, 27
	s_add_i32 s2, s1, s2
	s_ashr_i32 s3, s2, 5
	s_and_b32 s2, s2, 0xffe0
	s_sub_i32 s1, s1, s2
	s_bfe_i32 s2, s1, 0x80000
	s_bfe_u32 s2, s2, 0x3000c
	s_add_i32 s4, s1, s2
	s_bfe_i32 s2, s4, 0x80000
	s_and_b32 s4, s4, 0xf8
	s_sub_i32 s1, s1, s4
	s_lshl_b32 s3, s3, 3
	s_sext_i32_i8 s1, s1
	s_lshr_b32 s0, s5, 3
	s_sext_i32_i16 s5, s2
	s_add_i32 s1, s3, s1
	v_writelane_b32 v254, s1, 42
	s_ashr_i32 s1, s5, 3
	v_writelane_b32 v254, s1, 43
	s_mov_b32 s4, s6
	s_lshr_b32 s2, s5, 3
	v_writelane_b32 v254, s4, 44
	s_bfe_i64 s[0:1], s[0:1], 0x100000
	s_ashr_i32 s7, s6, 31
	v_writelane_b32 v254, s5, 45
	s_lshl_b64 s[0:1], s[0:1], 19
	s_lshl_b64 s[4:5], s[6:7], 19
	v_writelane_b32 v254, s0, 46
	v_mov_b32_e32 v16, 0xff800000
	v_mov_b64_e32 v[180:181], 0xaff
	v_writelane_b32 v254, s1, 47
	s_add_u32 s0, s84, s4
	s_addc_u32 s1, s85, s5
	s_add_u32 s4, s0, 0x40000
	v_writelane_b32 v254, s0, 48
	s_addc_u32 s5, s1, 0
	s_lshl_b32 s33, s33, 8
	v_writelane_b32 v254, s1, 49
	v_writelane_b32 v254, s4, 50
	s_bfe_i64 s[0:1], s[2:3], 0x100000
	s_add_u32 s82, s14, 0x10400
	v_writelane_b32 v254, s5, 51
	v_writelane_b32 v254, s0, 52
	s_addc_u32 s83, s15, 0
	s_mov_b32 s54, 0xff800000
	v_writelane_b32 v254, s1, 53
	s_add_i32 s0, 0, 0x20200
	v_writelane_b32 v254, s0, 54
	s_add_i32 s0, 0, 0x20204
	v_writelane_b32 v254, s0, 55
	s_add_i32 s0, 0, 0x207d0
	v_writelane_b32 v254, s0, 56
	s_add_i32 s0, 0, 0x207e0
	v_writelane_b32 v254, s0, 57
	s_add_i32 s0, 0, 0x20450
	v_writelane_b32 v254, s0, 58
	s_add_i32 s0, 0, 0x20458
	v_writelane_b32 v254, s0, 59
	s_add_i32 s0, 0, 0x20460
	v_writelane_b32 v254, s0, 60
	s_add_i32 s0, 0, 0x20468
	v_writelane_b32 v254, s0, 61
	s_add_i32 s0, 0, 0x20448
	v_writelane_b32 v254, s0, 62
	s_add_i32 s0, 0, 0x1e00
	v_writelane_b32 v254, s0, 63
	s_add_i32 s0, 0, 0x1e10
	v_writelane_b32 v255, s0, 0
	s_add_i32 s0, 0, 0x1e20
	v_writelane_b32 v255, s0, 1
	s_add_i32 s0, 0, 0x1e30
	v_writelane_b32 v255, s0, 2
	v_writelane_b32 v255, s74, 3
	s_movk_i32 s86, 0x201
	s_movk_i32 s97, 0x81
	v_writelane_b32 v255, s75, 4
	v_writelane_b32 v255, s55, 5
	v_writelane_b32 v255, s59, 6
	v_writelane_b32 v255, s60, 7
	v_writelane_b32 v255, s62, 8
	s_movk_i32 s78, 0x1600
	s_mov_b32 s89, 0
	v_writelane_b32 v255, s63, 9
	v_writelane_b32 v255, s64, 10
	s_mov_b64 s[92:93], 0x80
	s_mov_b64 s[90:91], 0xe00
	v_writelane_b32 v255, s65, 11
	v_writelane_b32 v255, s57, 12
	v_writelane_b32 v255, s66, 13
	s_barrier
	s_nop 0
	v_writelane_b32 v255, s67, 14
	v_writelane_b32 v255, s68, 15
	s_nop 1
	v_writelane_b32 v255, s69, 16
	v_writelane_b32 v255, s58, 17
	v_writelane_b32 v255, s61, 18
	v_writelane_b32 v255, s70, 19
	v_writelane_b32 v255, s72, 20
	s_nop 1
	v_writelane_b32 v255, s73, 21
	v_writelane_b32 v255, s77, 22
	v_writelane_b32 v255, s80, 23
	v_readlane_b32 s100, v254, 7
	s_and_b32 s101, s74, 7
	s_lshl_b32 s101, s101, 22
	s_cmp_eq_u32 s100, 0x100
	s_cselect_b32 s101, s101, 0
	v_writelane_b32 v255, s101, 43
	s_add_u32 s100, s66, s101
	s_addc_u32 s101, s67, 0
	v_writelane_b32 v255, s100, 41
	v_writelane_b32 v255, s101, 42
	s_branch .LBB0_472

.Lxb1_known:
	s_cmp_eq_u32 s2, 2
	s_cbranch_scc0 .Lxb1_slow
	s_branch .Lxb1_fast

.LBB0_577:
	s_cmp_eq_u32 s47, 1
	s_waitcnt lgkmcnt(0)
	v_lshl_or_b32 v170, s47, 8, v200
	s_cselect_b64 s[0:1], -1, 0
	s_cmp_eq_u32 s47, 4
	v_ashrrev_i32_e32 v171, 31, v170
	s_cselect_b64 s[2:3], -1, 0
	v_readlane_b32 s100, v255, 41
	v_readlane_b32 s101, v255, 42
	s_nop 1
	v_lshl_add_u64 v[170:171], v[170:171], 1, s[100:101]
	s_or_b64 vcc, s[0:1], s[2:3]
	v_mad_u64_u32 v[182:183], s[0:1], v150, s76, v[170:171]
	v_mov_b32_e32 v135, 0x3e38aa3b
	v_mov_b32_e32 v172, v183
	v_cndmask_b32_e32 v136, 1.0, v135, vcc
	v_mad_u64_u32 v[172:173], s[0:1], v151, s76, v[172:173]
	v_mov_b32_e32 v183, v172
	v_pk_mul_f32 v[174:175], v[136:137], v[132:133] op_sel_hi:[0,1]
	v_pk_mul_f32 v[172:173], v[136:137], v[130:131] op_sel_hi:[0,1]
	v_pk_mul_f32 v[184:185], v[136:137], v[128:129] op_sel_hi:[0,1]
	v_pk_mul_f32 v[186:187], v[136:137], v[126:127] op_sel_hi:[0,1]
	v_cvt_pk_bf16_f32 v172, v172, v173
	v_cvt_pk_bf16_f32 v173, v174, v175
	v_cvt_pk_bf16_f32 v174, v186, v187
	v_cvt_pk_bf16_f32 v175, v184, v185
	global_store_dwordx4 v[182:183], v[172:175], off
	v_pk_mul_f32 v[184:185], v[136:137], v[120:121] op_sel_hi:[0,1]
	v_pk_mul_f32 v[186:187], v[136:137], v[118:119] op_sel_hi:[0,1]
	v_pk_mul_f32 v[174:175], v[136:137], v[124:125] op_sel_hi:[0,1]
	v_pk_mul_f32 v[172:173], v[136:137], v[122:123] op_sel_hi:[0,1]
	v_cvt_pk_bf16_f32 v172, v172, v173
	v_cvt_pk_bf16_f32 v173, v174, v175
	v_cvt_pk_bf16_f32 v174, v186, v187
	v_cvt_pk_bf16_f32 v175, v184, v185
	global_store_dwordx4 v[182:183], v[172:175], off offset:256
	v_cndmask_b32_e64 v135, 0, 1, s[30:31]
	v_pk_mul_f32 v[116:117], v[116:117], v[168:169] op_sel_hi:[1,0]
	v_pk_mul_f32 v[114:115], v[114:115], v[168:169] op_sel_hi:[1,0]
	v_pk_mul_f32 v[112:113], v[112:113], v[168:169] op_sel_hi:[1,0]
	v_pk_mul_f32 v[110:111], v[110:111], v[168:169] op_sel_hi:[1,0]
	v_pk_mul_f32 v[108:109], v[108:109], v[168:169] op_sel_hi:[1,0]
	v_pk_mul_f32 v[106:107], v[106:107], v[168:169] op_sel_hi:[1,0]
	v_pk_mul_f32 v[104:105], v[104:105], v[168:169] op_sel_hi:[1,0]
	v_cmp_ne_u32_e64 s[0:1], 1, v135
	s_andn2_b64 vcc, exec, s[30:31]
	v_pk_mul_f32 v[102:103], v[102:103], v[168:169] op_sel_hi:[1,0]
	s_cbranch_vccnz .LBB0_581
	ds_bpermute_b32 v172, v192, v114
	ds_bpermute_b32 v173, v192, v115
	ds_bpermute_b32 v168, v192, v116
	ds_bpermute_b32 v169, v192, v117
	ds_bpermute_b32 v182, v192, v110
	ds_bpermute_b32 v183, v192, v111
	ds_bpermute_b32 v174, v192, v112
	ds_bpermute_b32 v175, v192, v113
	ds_bpermute_b32 v186, v192, v106
	ds_bpermute_b32 v187, v192, v107
	ds_bpermute_b32 v184, v192, v108
	ds_bpermute_b32 v185, v192, v109
	ds_bpermute_b32 v188, v192, v102
	ds_bpermute_b32 v189, v192, v103
	ds_bpermute_b32 v190, v192, v104
	ds_bpermute_b32 v191, v192, v105
	s_and_saveexec_b64 s[30:31], s[6:7]
	s_cbranch_execz .LBB0_580
	v_lshlrev_b64 v[202:203], 6, v[156:157]
	v_lshl_add_u64 v[214:215], s[72:73], 0, v[202:203]
	global_load_dwordx4 v[202:205], v[214:215], off
	global_load_dwordx4 v[206:209], v[214:215], off offset:32
	global_load_dwordx4 v[210:213], v[214:215], off offset:16
	s_nop 0
	global_load_dwordx4 v[214:217], v[214:215], off offset:48
	s_waitcnt vmcnt(0)
	v_xor_b32_e32 v135, 0x80000000, v214
	v_xor_b32_e32 v137, 0x80000000, v215
	v_xor_b32_e32 v151, 0x80000000, v216
	v_xor_b32_e32 v157, 0x80000000, v217
	v_cndmask_b32_e64 v217, v217, v157, s[4:5]
	v_cndmask_b32_e64 v216, v216, v151, s[4:5]
	v_cndmask_b32_e64 v215, v215, v137, s[4:5]
	v_cndmask_b32_e64 v214, v214, v135, s[4:5]
	s_waitcnt lgkmcnt(2)
	v_pk_mul_f32 v[188:189], v[214:215], v[188:189]
	s_waitcnt lgkmcnt(0)
	v_pk_mul_f32 v[190:191], v[216:217], v[190:191]
	v_xor_b32_e32 v135, 0x80000000, v206
	v_xor_b32_e32 v137, 0x80000000, v207
	v_xor_b32_e32 v151, 0x80000000, v208
	v_xor_b32_e32 v157, 0x80000000, v209
	v_pk_fma_f32 v[104:105], v[104:105], v[212:213], v[190:191]
	v_pk_fma_f32 v[102:103], v[102:103], v[210:211], v[188:189]
	v_cndmask_b32_e64 v189, v209, v157, s[4:5]
	v_cndmask_b32_e64 v188, v208, v151, s[4:5]
	v_cndmask_b32_e64 v191, v207, v137, s[4:5]
	v_cndmask_b32_e64 v190, v206, v135, s[4:5]
	v_pk_mul_f32 v[186:187], v[190:191], v[186:187]
	v_pk_mul_f32 v[184:185], v[188:189], v[184:185]
	v_pk_mul_f32 v[182:183], v[214:215], v[182:183]
	v_pk_mul_f32 v[174:175], v[216:217], v[174:175]
	v_pk_mul_f32 v[172:173], v[190:191], v[172:173]
	v_pk_mul_f32 v[168:169], v[188:189], v[168:169]
	v_pk_fma_f32 v[108:109], v[108:109], v[204:205], v[184:185]
	v_pk_fma_f32 v[106:107], v[106:107], v[202:203], v[186:187]
	v_pk_fma_f32 v[112:113], v[112:113], v[212:213], v[174:175]
	v_pk_fma_f32 v[110:111], v[110:111], v[210:211], v[182:183]
	v_pk_fma_f32 v[116:117], v[116:117], v[204:205], v[168:169]
	v_pk_fma_f32 v[114:115], v[114:115], v[202:203], v[172:173]

.LBB0_673:
	s_and_b64 vcc, exec, s[0:1]
	s_cbranch_vccz .LBB0_666
	s_cmpk_gt_i32 s13, 0x3ff
	s_mov_b64 s[0:1], -1
	s_cbranch_scc0 .LBB0_723
	s_cmpk_gt_u32 s13, 0x5ff
	s_cbranch_scc0 .LBB0_699
	s_add_i32 s14, s13, 0xfffffa00
	s_lshl_b32 s0, s14, 5
	v_mov_b32_e32 v46, v240
	s_and_b32 s1, s0, 0x7e0
	s_sub_i32 s10, 29, s1
	s_sub_i32 s11, s0, 30
	s_movk_i32 s0, 0x7c0
	v_ashrrev_i32_e32 v17, 5, v46
	v_cmp_gt_i32_e64 s[0:1], s0, v46
	v_cmp_lt_i32_e32 vcc, s10, v17
	v_lshlrev_b32_e32 v0, 3, v46
	s_and_b64 vcc, s[0:1], vcc
	v_and_b32_e32 v48, 0xf8, v0
	v_cndmask_b32_e32 v0, 30, v17, vcc
	v_add_u32_e32 v0, s11, v0
	v_readlane_b32 s100, v255, 41
	v_readlane_b32 s101, v255, 42
	s_nop 1
	v_mov_b64_e32 v[14:15], s[100:101]
	s_waitcnt vmcnt(0) lgkmcnt(0)
	v_mad_i64_i32 v[2:3], s[2:3], v0, s76, v[14:15]
	v_add_u32_e32 v10, 0x200, v46
	s_movk_i32 s2, 0x5c0
	v_ashrrev_i32_e32 v56, 5, v10
	v_cmp_gt_i32_e64 s[4:5], s2, v46
	v_cmp_lt_i32_e32 vcc, s10, v56
	s_and_b64 vcc, s[4:5], vcc
	v_add_u32_e32 v22, 0x400, v46
	v_cndmask_b32_e32 v10, 30, v56, vcc
	v_add_u32_e32 v10, s11, v10
	v_mad_i64_i32 v[10:11], s[2:3], v10, s76, v[14:15]
	s_movk_i32 s2, 0x3c0
	v_ashrrev_i32_e32 v57, 5, v22
	v_cmp_gt_i32_e64 s[6:7], s2, v46
	v_cmp_lt_i32_e32 vcc, s10, v57
	s_and_b64 vcc, s[6:7], vcc
	v_add_u32_e32 v30, 0x600, v46
	v_cndmask_b32_e32 v22, 30, v57, vcc
	v_add_u32_e32 v22, s11, v22
	v_mad_i64_i32 v[22:23], s[2:3], v22, s76, v[14:15]
	s_movk_i32 s2, 0x1c0
	v_ashrrev_i32_e32 v58, 5, v30
	v_cmp_gt_i32_e64 s[8:9], s2, v46
	v_cmp_lt_i32_e32 vcc, s10, v58
	s_and_b64 vcc, s[8:9], vcc
	v_lshlrev_b32_e32 v0, 1, v48
	v_cndmask_b32_e32 v30, 30, v58, vcc
	v_add_u32_e32 v30, s11, v30
	v_mad_i64_i32 v[14:15], s[2:3], v30, s76, v[14:15]
	v_lshl_add_u64 v[2:3], v[2:3], 0, v[0:1]
	v_lshl_add_u64 v[10:11], v[10:11], 0, v[0:1]
	v_lshl_add_u64 v[22:23], v[22:23], 0, v[0:1]
	v_lshl_add_u64 v[14:15], v[14:15], 0, v[0:1]
	v_lshl_add_u64 v[6:7], v[2:3], 0, s[90:91]
	v_lshl_add_u64 v[18:19], v[10:11], 0, s[90:91]
	v_lshl_add_u64 v[26:27], v[22:23], 0, s[90:91]
	v_lshl_add_u64 v[34:35], v[14:15], 0, s[90:91]
	v_readlane_b32 s2, v254, 58
	global_load_dwordx4 v[2:5], v[2:3], off offset:3584
	s_nop 0
	global_load_dwordx4 v[6:9], v[6:7], off offset:512
	s_nop 0
	global_load_dwordx4 v[10:13], v[10:11], off offset:3584
	s_nop 0
	global_load_dwordx4 v[18:21], v[18:19], off offset:512
	s_nop 0
	global_load_dwordx4 v[22:25], v[22:23], off offset:3584
	s_nop 0
	global_load_dwordx4 v[26:29], v[26:27], off offset:512
	s_nop 0
	global_load_dwordx4 v[30:33], v[14:15], off offset:3584
	s_nop 0
	global_load_dwordx4 v[34:37], v[34:35], off offset:512
	v_mov_b32_e32 v14, s2
	ds_read_b64 v[14:15], v14
	v_readlane_b32 s10, v255, 30
	v_readlane_b32 s16, v255, 35
	v_readlane_b32 s17, v255, 36
	v_and_b32_e32 v47, 63, v46
	s_waitcnt lgkmcnt(0)
	v_readfirstlane_b32 s2, v14
	v_readfirstlane_b32 s3, v15
	s_add_u32 s2, s2, s10
	v_readlane_b32 s10, v255, 29
	v_lshlrev_b32_e32 v14, 2, v46
	s_addc_u32 s3, s3, s10
	v_and_b32_e32 v14, 0x3fc, v14
	v_mov_b32_e32 v15, v1
	v_lshl_add_u64 v[38:39], s[2:3], 0, v[14:15]
	global_load_dword v59, v14, s[2:3]
	global_load_dword v60, v14, s[2:3] offset:1024
	global_load_dword v61, v14, s[2:3] offset:2048
	global_load_dword v62, v14, s[2:3] offset:3072
	s_movk_i32 s2, 0x1000
	v_add_co_u32_e32 v40, vcc, s2, v38
	s_movk_i32 s2, 0x2000
	s_nop 0
	v_addc_co_u32_e32 v41, vcc, 0, v39, vcc
	v_add_co_u32_e32 v42, vcc, s2, v38
	s_movk_i32 s2, 0x3000
	s_nop 0
	v_addc_co_u32_e32 v43, vcc, 0, v39, vcc
	global_load_dword v63, v[42:43], off offset:-4096
	global_load_dword v64, v[40:41], off offset:1024
	global_load_dword v65, v[40:41], off offset:2048
	global_load_dword v66, v[40:41], off offset:3072
	global_load_dword v67, v[42:43], off
	global_load_dword v68, v[42:43], off offset:1024
	global_load_dword v69, v[42:43], off offset:2048
	global_load_dword v70, v[42:43], off offset:3072
	v_add_co_u32_e32 v40, vcc, s2, v38
	s_movk_i32 s2, 0x5000
	s_nop 0
	v_addc_co_u32_e32 v41, vcc, 0, v39, vcc
	v_add_co_u32_e32 v42, vcc, s81, v38
	v_add_u32_e32 v92, 0, v14
	s_nop 0
	v_addc_co_u32_e32 v43, vcc, 0, v39, vcc
	global_load_dword v71, v[42:43], off offset:-4096
	global_load_dword v72, v[40:41], off offset:1024
	global_load_dword v73, v[40:41], off offset:2048
	global_load_dword v74, v[40:41], off offset:3072
	global_load_dword v75, v[42:43], off
	global_load_dword v76, v[42:43], off offset:1024
	global_load_dword v77, v[42:43], off offset:2048
	global_load_dword v78, v[42:43], off offset:3072
	v_add_co_u32_e32 v40, vcc, s2, v38
	s_movk_i32 s2, 0x6000
	s_nop 0
	v_addc_co_u32_e32 v41, vcc, 0, v39, vcc
	v_add_co_u32_e32 v42, vcc, s2, v38
	s_movk_i32 s2, 0x7000
	s_nop 0
	v_addc_co_u32_e32 v43, vcc, 0, v39, vcc
	v_add_co_u32_e32 v38, vcc, s2, v38
	v_readlane_b32 s2, v254, 59
	s_nop 0
	v_addc_co_u32_e32 v39, vcc, 0, v39, vcc
	v_mov_b32_e32 v15, s2
	global_load_dword v79, v[42:43], off offset:-4096
	global_load_dword v80, v[40:41], off offset:1024
	global_load_dword v81, v[40:41], off offset:2048
	global_load_dword v82, v[40:41], off offset:3072
	global_load_dword v83, v[42:43], off
	global_load_dword v84, v[42:43], off offset:1024
	global_load_dword v85, v[42:43], off offset:2048
	global_load_dword v86, v[42:43], off offset:3072
	global_load_dword v87, v[38:39], off
	global_load_dword v88, v[38:39], off offset:1024
	global_load_dword v89, v[38:39], off offset:2048
	ds_read_b64 v[38:39], v15
	v_cmp_lt_i32_e32 vcc, v243, v242
	v_readfirstlane_b32 s10, v46
	v_lshrrev_b32_e32 v46, 4, v46
	v_lshl_add_u32 v48, v48, 2, 0
	s_waitcnt lgkmcnt(0)
	v_readfirstlane_b32 s2, v38
	v_readfirstlane_b32 s3, v39
	s_add_u32 s2, s2, s16
	s_addc_u32 s3, s3, s17
	v_and_b32_e32 v91, 0x3ffff0, v46
	v_lshlrev_b32_e32 v46, 10, v17
	v_lshlrev_b32_e32 v49, 10, v56
	global_load_dword v90, v14, s[2:3]
	v_readlane_b32 s2, v254, 60
	v_cndmask_b32_e32 v14, v241, v243, vcc
	v_lshlrev_b32_e32 v94, 2, v14
	v_mov_b32_e32 v15, s2
	ds_read_b64 v[38:39], v15
	v_lshlrev_b32_e32 v15, 4, v47
	v_xor_b32_e32 v14, 2, v241
	v_cmp_lt_i32_e32 vcc, v14, v242
	v_add_u32_e32 v93, 0, v15
	s_waitcnt lgkmcnt(0)
	v_readfirstlane_b32 s2, v38
	v_readfirstlane_b32 s3, v39
	s_add_u32 s2, s2, s16
	s_addc_u32 s3, s3, s17
	v_cndmask_b32_e32 v14, v241, v14, vcc
	v_lshlrev_b32_e32 v95, 2, v14
	v_xor_b32_e32 v14, 4, v241
	global_load_dwordx4 v[38:41], v15, s[2:3]
	v_readlane_b32 s2, v254, 61
	v_cmp_lt_i32_e32 vcc, v14, v242
	v_lshlrev_b32_e32 v50, 10, v57
	v_mov_b32_e32 v42, s2
	ds_read_b64 v[42:43], v42
	v_cndmask_b32_e32 v14, v241, v14, vcc
	v_lshlrev_b32_e32 v96, 2, v14
	v_xor_b32_e32 v14, 8, v241
	v_cmp_lt_i32_e32 vcc, v14, v242
	s_waitcnt lgkmcnt(0)
	v_readfirstlane_b32 s2, v42
	v_readfirstlane_b32 s3, v43
	s_add_u32 s2, s2, s16
	s_addc_u32 s3, s3, s17
	v_cndmask_b32_e32 v14, v241, v14, vcc
	v_lshlrev_b32_e32 v97, 2, v14
	v_xor_b32_e32 v14, 16, v241
	global_load_dwordx4 v[42:45], v15, s[2:3]
	v_cmp_lt_i32_e32 vcc, v14, v242
	s_ashr_i32 s2, s10, 4
	s_and_b32 s16, s2, -4
	v_cndmask_b32_e32 v14, v241, v14, vcc
	v_lshlrev_b32_e32 v98, 2, v14
	v_xor_b32_e32 v14, 32, v241
	v_cmp_lt_i32_e32 vcc, v14, v242
	v_lshlrev_b32_e32 v51, 10, v58
	s_or_b32 s18, s16, 1
	v_cndmask_b32_e32 v14, v241, v14, vcc
	v_lshlrev_b32_e32 v99, 2, v14
	s_or_b32 s20, s16, 2
	s_or_b32 s22, s2, 3
	v_readlane_b32 s100, v255, 41
	v_readlane_b32 s101, v255, 42
	s_nop 1
	v_lshl_add_u64 v[14:15], s[100:101], 0, v[0:1]
	v_lshlrev_b32_e32 v0, 3, v47
	s_mov_b32 s15, 0
	s_lshl_b32 s17, s16, 10
	s_lshl_b32 s19, s18, 10
	s_lshl_b32 s21, s20, 10
	s_lshl_b32 s23, s22, 10
	v_lshl_add_u64 v[54:55], s[68:69], 0, v[0:1]
	v_add_u32_e32 v0, v48, v46
	v_add_u32_e32 v100, v48, v49
	v_add_u32_e32 v101, v48, v50
	v_add_u32_e32 v102, v48, v51

.LBB0_699:
	s_and_b64 vcc, exec, s[0:1]
	s_cbranch_vccz .LBB0_722
	v_readlane_b32 s0, v254, 62
	v_readlane_b32 s2, v255, 33
	v_readlane_b32 s3, v255, 34
	v_mov_b32_e32 v0, s0
	s_waitcnt vmcnt(0) lgkmcnt(0)
	ds_read_b64 v[2:3], v0
	v_mov_b32_e32 v24, v240
	s_waitcnt lgkmcnt(0)
	v_readfirstlane_b32 s1, v2
	v_readfirstlane_b32 s0, v3
	s_add_u32 s14, s1, s2
	s_addc_u32 s15, s0, s3
	s_add_i32 s2, s13, 0xfffffc00
	s_lshl_b32 s0, s2, 6
	s_and_b32 s1, s0, 0x7c0
	s_sub_i32 s17, 14, s1
	s_add_i32 s18, s0, -15
	v_ashrrev_i32_e32 v17, 5, v24
	s_movk_i32 s0, 0x9e0
	v_cmp_gt_i32_e64 s[0:1], s0, v24
	v_cmp_lt_i32_e32 vcc, s17, v17
	v_lshlrev_b32_e32 v25, 4, v24
	s_and_b64 vcc, s[0:1], vcc
	v_and_b32_e32 v0, 0x1f0, v25
	v_cndmask_b32_e32 v2, 15, v17, vcc
	v_readlane_b32 s100, v255, 41
	v_readlane_b32 s101, v255, 42
	s_nop 1
	v_lshl_add_u64 v[14:15], s[100:101], 0, v[0:1]
	v_add_u32_e32 v2, s18, v2
	v_mad_i64_i32 v[2:3], s[4:5], v2, s76, v[14:15]
	global_load_dwordx4 v[2:5], v[2:3], off
	v_add_u32_e32 v26, 0x200, v24
	v_ashrrev_i32_e32 v94, 5, v26
	s_movk_i32 s4, 0x7e0
	v_cmp_gt_i32_e64 s[4:5], s4, v24
	v_add_u32_e32 v27, 0x400, v24
	v_ashrrev_i32_e32 v95, 5, v27
	v_add_u32_e32 v28, 0x600, v24
	v_ashrrev_i32_e32 v96, 5, v28
	v_add_u32_e32 v29, 0x800, v24
	v_ashrrev_i32_e32 v97, 5, v29
	v_readfirstlane_b32 s16, v24
	v_and_b32_e32 v30, 31, v24
	v_bfe_u32 v31, v24, 5, 1
	v_and_b32_e32 v32, 7, v24
	v_bfe_u32 v33, v24, 1, 2
	v_lshlrev_b32_e32 v32, 6, v32
	v_lshlrev_b32_e32 v26, 4, v26
	v_lshlrev_b32_e32 v27, 4, v27
	v_lshlrev_b32_e32 v28, 4, v28
	v_lshlrev_b32_e32 v29, 4, v29
	v_and_b32_e32 v25, 0xfffffe00, v25
	v_and_b32_e32 v26, 0xfffffe00, v26
	v_and_b32_e32 v27, 0xfffffe00, v27
	v_and_b32_e32 v28, 0xfffffe00, v28
	v_and_b32_e32 v29, 0xfffffe00, v29
	s_mov_b32 s3, 0
	s_waitcnt vmcnt(0)
	v_cndmask_b32_e32 v5, 0, v5, vcc
	v_cndmask_b32_e32 v4, 0, v4, vcc
	v_cndmask_b32_e32 v3, 0, v3, vcc
	v_cndmask_b32_e32 v2, 0, v2, vcc
	v_cmp_lt_i32_e32 vcc, s17, v94
	s_and_b64 vcc, s[4:5], vcc
	s_nop 0
	v_cndmask_b32_e32 v6, 15, v94, vcc
	v_add_u32_e32 v6, s18, v6
	v_mad_i64_i32 v[6:7], s[6:7], v6, s76, v[14:15]
	global_load_dwordx4 v[6:9], v[6:7], off
	s_movk_i32 s6, 0x5e0
	v_cmp_gt_i32_e64 s[6:7], s6, v24
	s_waitcnt vmcnt(0)
	v_cndmask_b32_e32 v9, 0, v9, vcc
	v_cndmask_b32_e32 v8, 0, v8, vcc
	v_cndmask_b32_e32 v7, 0, v7, vcc
	v_cndmask_b32_e32 v6, 0, v6, vcc
	v_cmp_lt_i32_e32 vcc, s17, v95
	s_and_b64 vcc, s[6:7], vcc
	s_nop 0
	v_cndmask_b32_e32 v10, 15, v95, vcc
	v_add_u32_e32 v10, s18, v10
	v_mad_i64_i32 v[10:11], s[8:9], v10, s76, v[14:15]
	global_load_dwordx4 v[10:13], v[10:11], off
	s_movk_i32 s8, 0x3e0
	v_cmp_gt_i32_e64 s[8:9], s8, v24
	s_waitcnt vmcnt(0)
	v_cndmask_b32_e32 v13, 0, v13, vcc
	v_cndmask_b32_e32 v12, 0, v12, vcc
	v_cndmask_b32_e32 v11, 0, v11, vcc
	v_cndmask_b32_e32 v10, 0, v10, vcc
	v_cmp_lt_i32_e32 vcc, s17, v96
	s_and_b64 vcc, s[8:9], vcc
	s_nop 0
	v_cndmask_b32_e32 v18, 15, v96, vcc
	v_add_u32_e32 v18, s18, v18
	v_mad_i64_i32 v[18:19], s[10:11], v18, s76, v[14:15]
	global_load_dwordx4 v[18:21], v[18:19], off
	s_movk_i32 s10, 0x1e0
	v_cmp_gt_i32_e64 s[10:11], s10, v24
	s_waitcnt vmcnt(0)
	v_cndmask_b32_e32 v77, 0, v21, vcc
	v_cndmask_b32_e32 v76, 0, v20, vcc
	v_cndmask_b32_e32 v75, 0, v19, vcc
	v_cndmask_b32_e32 v74, 0, v18, vcc
	v_cmp_lt_i32_e32 vcc, s17, v97
	s_and_b64 vcc, s[10:11], vcc
	s_ashr_i32 s17, s16, 7
	v_cndmask_b32_e32 v18, 15, v97, vcc
	v_add_u32_e32 v18, s18, v18
	v_mad_i64_i32 v[18:19], s[18:19], v18, s76, v[14:15]
	global_load_dwordx4 v[18:21], v[18:19], off
	v_readlane_b32 s18, v255, 31
	v_readlane_b32 s19, v255, 32
	s_waitcnt vmcnt(0)
	v_cndmask_b32_e32 v87, 0, v19, vcc
	v_lshlrev_b32_e32 v19, 6, v30
	v_cndmask_b32_e32 v86, 0, v18, vcc
	v_lshlrev_b32_e32 v18, 3, v31
	v_lshl_or_b32 v22, s17, 12, v19
	v_or_b32_e32 v18, v22, v18
	v_ashrrev_i32_e32 v19, 31, v18
	v_cndmask_b32_e32 v89, 0, v21, vcc
	v_cndmask_b32_e32 v88, 0, v20, vcc
	v_lshl_add_u64 v[20:21], v[18:19], 1, s[18:19]
	global_load_dwordx4 v[50:53], v[20:21], off
	v_or_b32_e32 v20, 0x800, v18
	v_ashrrev_i32_e32 v21, 31, v20
	v_ashrrev_i32_e32 v19, 31, v22
	v_or_b32_e32 v22, 0x810, v18
	v_lshl_add_u64 v[20:21], v[20:21], 1, s[18:19]
	v_ashrrev_i32_e32 v23, 31, v22
	global_load_dwordx4 v[54:57], v[20:21], off
	v_lshl_add_u64 v[20:21], v[18:19], 1, s[18:19]
	v_lshl_add_u64 v[22:23], v[22:23], 1, s[18:19]
	global_load_dwordx4 v[58:61], v[20:21], off offset:32
	global_load_dwordx4 v[62:65], v[22:23], off
	global_load_dwordx4 v[66:69], v[20:21], off offset:64
	v_or_b32_e32 v22, 0x820, v18
	v_or_b32_e32 v18, 0x830, v18
	v_ashrrev_i32_e32 v23, 31, v22
	v_ashrrev_i32_e32 v19, 31, v18
	v_lshl_add_u64 v[22:23], v[22:23], 1, s[18:19]
	v_lshl_add_u64 v[18:19], v[18:19], 1, s[18:19]
	global_load_dwordx4 v[70:73], v[22:23], off
	global_load_dwordx4 v[78:81], v[20:21], off offset:96
	global_load_dwordx4 v[82:85], v[18:19], off
	v_lshl_or_b32 v18, s17, 6, v30
	v_ashrrev_i32_e32 v19, 31, v18
	v_lshl_add_u64 v[20:21], v[18:19], 2, s[14:15]
	global_load_dword v98, v[20:21], off
	global_load_dword v99, v[20:21], off offset:128
	v_ashrrev_i32_e32 v21, 3, v24
	s_movk_i32 s18, 0x90
	s_mulk_i32 s17, 0x2400
	v_add_u32_e32 v20, 0, v0
	v_lshlrev_b32_e64 v0, v33, 2
	v_add_u32_e32 v100, 1, v21
	v_lshlrev_b32_e32 v34, 9, v21
	v_mul_u32_u24_e32 v33, 0x2400, v33
	v_mul_lo_u32 v21, v21, s18
	s_add_i32 s14, s17, 0
	v_or_b32_e32 v22, 32, v18
	v_add3_u32 v21, 0, v33, v21
	s_lshr_b32 s15, s16, 1
	v_mov_b32_e32 v33, s14
	v_lshl_add_u64 v[90:91], v[18:19], 1, s[68:69]
	v_or_b32_e32 v18, v34, v32
	v_readlane_b32 s14, v254, 63
	s_and_b32 s15, s15, 32
	v_lshlrev_b32_e32 v24, 6, v24
	v_add_u32_e32 v102, s14, v18
	v_readlane_b32 s14, v255, 0
	v_or_b32_e32 v30, s15, v30
	v_ashrrev_i32_e32 v23, 31, v22
	v_add_u32_e32 v103, s14, v18
	v_readlane_b32 s14, v255, 1
	v_add_u32_e32 v35, 0, v34
	v_and_b32_e32 v24, 64, v24
	v_mad_u32_u24 v30, v30, s18, v33
	v_lshlrev_b32_e32 v33, 4, v31
	v_add_u32_e32 v104, s14, v18
	v_readlane_b32 s14, v255, 2
	v_lshl_or_b32 v101, v31, 2, s15
	v_lshl_add_u64 v[92:93], v[22:23], 1, s[68:69]
	v_add_u32_e32 v105, s14, v18
	v_add_u32_e32 v106, v20, v25
	v_add_u32_e32 v107, v20, v26
	v_add_u32_e32 v108, v20, v27
	v_add_u32_e32 v109, v20, v28
	v_add_u32_e32 v110, v20, v29
	v_add_u32_e32 v111, v30, v33
	v_add_u32_e32 v112, v35, v32
	v_add_u32_e32 v113, v21, v24

.LBB0_735:
	s_lshr_b32 s0, s13, 7
	s_lshr_b32 s1, s13, 9
	s_add_i32 s0, s0, s1
	s_lshl_b32 s1, s44, 6
	s_lshl_b32 s2, s45, 11
	s_and_b32 s0, s0, 1
	s_and_b32 s1, s1, 0xc0
	v_writelane_b32 v254, s2, 9
	s_lshl_b32 s94, s46, 8
	s_lshl_b32 s95, s46, 1
	v_writelane_b32 v255, s1, 38
	v_writelane_b32 v254, s3, 10
	s_cmp_eq_u32 s0, 0
	s_mov_b64 s[4:5], -1
	s_mul_i32 s42, s46, 0x90000
	s_cbranch_scc1 .LBB0_788
	v_readlane_b32 s0, v255, 38
	v_readlane_b32 s2, v255, 41
	v_readlane_b32 s3, v255, 42
	s_or_b32 s47, s95, 1
	s_lshl_b32 s0, s0, 1
	s_waitcnt vmcnt(0)
	v_mov_b32_e32 v10, v240
	s_add_u32 s0, s2, s0
	s_addc_u32 s1, s3, 0
	v_readfirstlane_b32 s2, v10
	v_readlane_b32 s10, v254, 9
	s_ashr_i32 s2, s2, 6
	v_bfe_u32 v0, v10, 3, 3
	v_readlane_b32 s11, v254, 10
	v_lshl_or_b32 v2, s2, 3, v0
	s_mov_b32 s11, s89
	s_waitcnt lgkmcnt(0)
	v_ashrrev_i32_e32 v3, 31, v2
	v_lshl_add_u64 v[4:5], v[2:3], 0, s[10:11]
	v_ashrrev_i32_e32 v2, 1, v2
	v_mov_b64_e32 v[6:7], s[0:1]
	v_xor_b32_e32 v0, v2, v10
	v_mad_u64_u32 v[8:9], s[0:1], v4, s76, v[6:7]
	v_lshlrev_b32_e32 v0, 4, v0
	s_mov_b32 s43, s89
	v_mad_i32_i24 v9, v5, s76, v9
	v_and_b32_e32 v0, 0x70, v0
	s_lshl_b32 s0, s2, 10
	v_and_b32_e32 v3, 7, v10
	v_lshl_add_u64 v[184:185], v[8:9], 0, v[0:1]
	v_lshlrev_b32_e32 v0, 2, v2
	s_add_i32 s49, s0, 0
	s_lshl_b64 s[0:1], s[42:43], 1
	s_lshl_b32 s48, s2, 5
	v_bitop3_b32 v0, v0, v3, 4 bitop3:0x6c
	v_lshl_add_u64 v[2:3], v[184:185], 0, s[0:1]
	s_mov_b64 s[2:3], 0xa00
	v_lshlrev_b32_e32 v0, 4, v0
	v_lshl_add_u64 v[4:5], v[2:3], 0, s[2:3]
	s_mov_b32 m0, s49
	s_mov_b64 s[4:5], 0x48a00
	v_lshl_add_u64 v[186:187], v[8:9], 0, v[0:1]
	global_load_lds_dwordx4 v[4:5], off
	v_lshl_add_u64 v[2:3], v[2:3], 0, s[4:5]
	s_add_i32 m0, s49, 0x2000
	s_mov_b64 s[6:7], 0xc00
	global_load_lds_dwordx4 v[2:3], off
	v_lshl_add_u64 v[2:3], v[186:187], 0, s[0:1]
	s_add_i32 s88, s42, 0x48000
	v_lshl_add_u64 v[4:5], v[2:3], 0, s[6:7]
	s_add_i32 m0, s49, 0x4000
	s_mov_b64 s[8:9], 0x48c00
	global_load_lds_dwordx4 v[4:5], off
	v_lshl_add_u64 v[2:3], v[2:3], 0, s[8:9]
	s_add_i32 m0, s49, 0x6000
	s_lshl_b64 s[0:1], s[88:89], 1
	global_load_lds_dwordx4 v[2:3], off
	v_lshl_add_u64 v[2:3], v[184:185], 0, s[0:1]
	s_add_i32 m0, s49, 0x8000
	v_lshl_add_u64 v[4:5], v[2:3], 0, s[2:3]
	global_load_lds_dwordx4 v[4:5], off
	v_lshl_add_u64 v[2:3], v[2:3], 0, s[4:5]
	s_add_i32 m0, s49, 0xa000
	v_and_b32_e32 v11, 31, v10
	s_add_i32 s48, s48, s94
	global_load_lds_dwordx4 v[2:3], off
	v_lshl_add_u64 v[2:3], v[186:187], 0, s[0:1]
	v_or_b32_e32 v182, s48, v11
	v_lshl_add_u64 v[4:5], v[2:3], 0, s[6:7]
	s_add_i32 m0, s49, 0xc000
	v_lshl_add_u64 v[2:3], v[2:3], 0, s[8:9]
	global_load_lds_dwordx4 v[4:5], off
	s_add_i32 m0, s49, 0xe000
	v_ashrrev_i32_e32 v183, 31, v182
	s_mov_b32 s0, s10
	global_load_lds_dwordx4 v[2:3], off
	v_writelane_b32 v254, s0, 9
	v_lshl_add_u64 v[2:3], v[182:183], 0, s[10:11]
	v_bfe_u32 v12, v10, 5, 1
	v_writelane_b32 v254, s1, 10
	v_mad_u64_u32 v[4:5], s[0:1], v2, s76, v[6:7]
	v_mad_i32_i24 v5, v3, s76, v5
	v_lshlrev_b32_e32 v0, 4, v12
	v_lshl_add_u64 v[2:3], v[4:5], 0, v[0:1]
	global_load_dwordx4 v[160:163], v[2:3], off offset:2048
	global_load_dwordx4 v[164:167], v[2:3], off offset:2080
	global_load_dwordx4 v[168:171], v[2:3], off offset:2112
	global_load_dwordx4 v[172:175], v[2:3], off offset:2144
	v_lshlrev_b32_e32 v183, 2, v12
	v_lshrrev_b32_e32 v0, 2, v10
	v_and_or_b32 v0, v0, 3, v183
	v_lshlrev_b32_e32 v2, 3, v10
	v_lshlrev_b32_e32 v189, 7, v0
	v_lshlrev_b32_e32 v0, 1, v10
	v_and_b32_e32 v3, 24, v2
	v_and_or_b32 v190, v0, 32, v3
	v_lshrrev_b32_e32 v0, 1, v10
	v_and_b32_e32 v188, 64, v2
	v_bitop3_b32 v191, v190, v2, 64 bitop3:0x72
	v_bfe_u32 v2, v10, 1, 3
	v_lshlrev_b32_e32 v3, 7, v11
	v_bitop3_b32 v0, v12, v0, 7 bitop3:0x78
	v_lshl_or_b32 v192, v0, 4, v3
	v_bitop3_b32 v0, v12, v2, 2 bitop3:0x36
	v_lshl_or_b32 v193, v0, 4, v3
	v_bitop3_b32 v0, v12, v2, 4 bitop3:0x36
	v_lshl_or_b32 v194, v0, 4, v3
	v_bitop3_b32 v0, v12, v2, 6 bitop3:0x36
	v_lshl_or_b32 v195, v0, 4, v3
	v_sub_u32_e32 v0, v10, v183
	v_and_b32_e32 v0, 15, v0
	v_subrev_co_u32_e64 v3, s[4:5], 1, v0
	v_and_b32_e32 v4, 15, v3
	v_and_b32_e32 v3, 3, v3
	v_mov_b32_e32 v208, 0xff800000
	v_cmp_eq_u32_e32 vcc, 0, v3
	v_cmp_eq_u32_e64 s[6:7], 0, v4
	v_and_b32_e32 v2, 3, v10
	v_cndmask_b32_e64 v3, v208, 0, vcc
	v_cndmask_b32_e64 v197, v3, 1.0, s[6:7]
	v_add_u32_e32 v3, -2, v0
	v_and_b32_e32 v4, 15, v3
	v_and_b32_e32 v3, 3, v3
	v_cmp_eq_u32_e32 vcc, 0, v3
	v_cmp_eq_u32_e64 s[8:9], 0, v4
	v_cmp_eq_u32_e64 s[0:1], 0, v2
	v_cndmask_b32_e64 v3, v208, 0, vcc
	v_cndmask_b32_e64 v198, v3, 1.0, s[8:9]
	v_add_u32_e32 v3, -3, v0
	v_and_b32_e32 v4, 15, v3
	v_and_b32_e32 v3, 3, v3
	v_cndmask_b32_e64 v2, v208, 0, s[0:1]
	v_cmp_eq_u32_e32 vcc, 0, v3
	v_cmp_eq_u32_e64 s[14:15], 8, v0
	v_cndmask_b32_e64 v196, v2, 1.0, s[4:5]
	v_cndmask_b32_e64 v3, v208, 0, vcc
	v_cmp_eq_u32_e64 s[10:11], 0, v4
	v_cndmask_b32_e64 v200, v2, 1.0, s[14:15]
	v_add_u32_e32 v2, -9, v0
	v_cndmask_b32_e64 v199, v3, 1.0, s[10:11]
	v_and_b32_e32 v3, 15, v2
	v_and_b32_e32 v2, 3, v2
	v_cmp_eq_u32_e32 vcc, 0, v2
	v_cmp_eq_u32_e64 s[16:17], 0, v3
	v_mov_b32_e32 v14, v1
	v_cndmask_b32_e64 v2, v208, 0, vcc
	v_cndmask_b32_e64 v201, v2, 1.0, s[16:17]
	v_add_u32_e32 v2, -10, v0
	v_and_b32_e32 v3, 15, v2
	v_and_b32_e32 v2, 3, v2
	v_cmp_eq_u32_e32 vcc, 0, v2
	v_cmp_eq_u32_e64 s[18:19], 0, v3
	v_mov_b32_e32 v15, v1
	v_cndmask_b32_e64 v2, v208, 0, vcc
	v_cndmask_b32_e64 v202, v2, 1.0, s[18:19]
	v_add_u32_e32 v2, -11, v0
	v_and_b32_e32 v3, 15, v2
	v_and_b32_e32 v2, 3, v2
	v_cmp_eq_u32_e32 vcc, 0, v2
	v_cmp_eq_u32_e64 s[20:21], 0, v3
	v_mov_b32_e32 v4, v1
	v_cndmask_b32_e64 v2, v208, 0, vcc
	v_cndmask_b32_e64 v203, v2, 1.0, s[20:21]
	v_subrev_u32_e32 v2, 17, v0
	v_and_b32_e32 v3, 15, v2
	v_and_b32_e32 v2, 3, v2
	v_cmp_eq_u32_e32 vcc, 0, v2
	v_cmp_eq_u32_e64 s[22:23], 0, v3
	v_mov_b32_e32 v5, v1
	v_cndmask_b32_e64 v2, v208, 0, vcc
	v_cndmask_b32_e64 v204, v2, 1.0, s[22:23]
	v_subrev_u32_e32 v2, 18, v0
	v_and_b32_e32 v3, 15, v2
	v_and_b32_e32 v2, 3, v2
	v_cmp_eq_u32_e32 vcc, 0, v2
	v_cmp_eq_u32_e64 s[24:25], 0, v3
	v_mov_b32_e32 v6, v1
	v_cndmask_b32_e64 v2, v208, 0, vcc
	v_cndmask_b32_e64 v205, v2, 1.0, s[24:25]
	v_subrev_u32_e32 v2, 19, v0
	v_and_b32_e32 v3, 15, v2
	v_and_b32_e32 v2, 3, v2
	v_cmp_eq_u32_e32 vcc, 0, v2
	v_cmp_eq_u32_e64 s[26:27], 0, v3
	v_mov_b32_e32 v7, v1
	v_cndmask_b32_e64 v2, v208, 0, vcc
	v_cndmask_b32_e64 v206, v2, 1.0, s[26:27]
	v_subrev_u32_e32 v2, 25, v0
	v_and_b32_e32 v3, 15, v2
	v_and_b32_e32 v2, 3, v2
	v_cmp_eq_u32_e32 vcc, 0, v2
	v_cmp_eq_u32_e64 s[28:29], 0, v3
	v_mov_b32_e32 v8, v1
	v_cndmask_b32_e64 v2, v208, 0, vcc
	v_cndmask_b32_e64 v207, v2, 1.0, s[28:29]
	v_subrev_u32_e32 v2, 26, v0
	v_and_b32_e32 v3, 15, v2
	v_and_b32_e32 v2, 3, v2
	v_cmp_eq_u32_e32 vcc, 0, v2
	v_cmp_eq_u32_e64 s[30:31], 0, v3
	v_subrev_u32_e32 v0, 27, v0
	v_cndmask_b32_e64 v2, v208, 0, vcc
	v_cndmask_b32_e64 v209, v2, 1.0, s[30:31]
	v_and_b32_e32 v2, 15, v0
	v_and_b32_e32 v0, 3, v0
	v_cmp_eq_u32_e32 vcc, 0, v0
	v_cmp_eq_u32_e64 s[34:35], 0, v2
	v_mov_b32_e32 v2, v1
	v_cndmask_b32_e64 v0, v208, 0, vcc
	v_cndmask_b32_e64 v210, v0, 1.0, s[34:35]
	v_mov_b32_e32 v0, v1
	v_mov_b32_e32 v3, v1
	v_mov_b32_e32 v9, v1
	v_mov_b32_e32 v10, v1
	v_mov_b32_e32 v11, v1
	v_mov_b32_e32 v12, v1
	v_mov_b32_e32 v13, v1
	v_mov_b64_e32 v[62:63], v[14:15]
	v_mov_b64_e32 v[46:47], v[14:15]
	s_mov_b64 s[62:63], s[68:69]
	s_mov_b64 s[68:69], s[72:73]
	s_mov_b64 s[72:73], s[64:65]
	s_mov_b64 s[58:59], 0xa00
	s_mov_b64 s[60:61], 0x48a00
	s_mov_b64 s[70:71], 0xc00
	s_mov_b64 s[64:65], 0x48c00
	s_mov_b32 s43, 0
	s_or_b32 s50, s48, 31
	v_or_b32_e32 v211, 2, v183
	v_or_b32_e32 v212, 3, v183
	v_or_b32_e32 v213, 8, v183
	v_or_b32_e32 v214, 9, v183
	v_or_b32_e32 v215, 10, v183
	v_or_b32_e32 v216, 11, v183
	v_or_b32_e32 v217, 16, v183
	v_or_b32_e32 v218, 17, v183
	v_or_b32_e32 v219, 18, v183
	v_or_b32_e32 v220, 19, v183
	v_or_b32_e32 v221, 24, v183
	v_or_b32_e32 v222, 25, v183
	v_or_b32_e32 v223, 26, v183
	v_or_b32_e32 v224, 27, v183
	v_mov_b32_e32 v225, 0
	v_mov_b64_e32 v[60:61], v[12:13]
	v_mov_b64_e32 v[58:59], v[10:11]
	v_mov_b64_e32 v[56:57], v[8:9]
	v_mov_b64_e32 v[54:55], v[6:7]
	v_mov_b64_e32 v[52:53], v[4:5]
	v_mov_b64_e32 v[50:51], v[2:3]
	v_mov_b64_e32 v[48:49], v[0:1]
	v_mov_b64_e32 v[44:45], v[12:13]
	v_mov_b64_e32 v[42:43], v[10:11]
	v_mov_b64_e32 v[40:41], v[8:9]
	v_mov_b64_e32 v[38:39], v[6:7]
	v_mov_b64_e32 v[36:37], v[4:5]
	v_mov_b64_e32 v[34:35], v[2:3]
	v_mov_b64_e32 v[32:33], v[0:1]
	s_waitcnt vmcnt(0) lgkmcnt(0)
	s_barrier
	s_cmp_lt_u32 s43, s95
	s_mov_b64 s[36:37], -1
	s_cbranch_scc1 .LBB0_739
	s_branch .LBB0_738

.LBB0_788:
	s_mov_b64 s[0:1], 0x400
	s_and_b64 vcc, exec, s[4:5]
	s_cbranch_vccz .LBB0_665
	s_lshl_b32 s0, -1, s46
	s_not_b32 s6, s0
	v_readlane_b32 s0, v255, 38
	s_lshl_b32 s0, s0, 1
	v_mov_b32_e32 v17, v240
	v_readlane_b32 s100, v255, 41
	v_readlane_b32 s101, v255, 42
	s_nop 1
	s_add_u32 s0, s100, s0
	s_addc_u32 s1, s101, 0
	v_readfirstlane_b32 s2, v17
	s_ashr_i32 s2, s2, 6
	s_lshl_b32 s8, s2, 3
	v_readlane_b32 s20, v254, 9
	v_bfe_u32 v127, v17, 3, 3
	v_readlane_b32 s21, v254, 10
	s_waitcnt vmcnt(0)
	v_or_b32_e32 v2, s8, v127
	s_mov_b32 s21, s89
	s_waitcnt lgkmcnt(0)
	v_ashrrev_i32_e32 v3, 31, v2
	v_lshl_add_u64 v[4:5], v[2:3], 0, s[20:21]
	v_mov_b64_e32 v[6:7], s[0:1]
	v_mad_u64_u32 v[8:9], s[0:1], v4, s76, v[6:7]
	v_mad_i32_i24 v9, v5, s76, v9
	v_ashrrev_i32_e32 v5, 1, v2
	v_xor_b32_e32 v126, v5, v17
	v_lshlrev_b32_e32 v0, 4, v126
	v_and_b32_e32 v0, 0x70, v0
	v_and_b32_e32 v4, 7, v17
	v_lshl_add_u64 v[2:3], v[8:9], 0, v[0:1]
	v_lshlrev_b32_e32 v0, 2, v5
	s_mov_b32 s43, s89
	v_bitop3_b32 v0, v0, v4, 4 bitop3:0x6c
	s_lshl_b32 s75, s2, 5
	s_lshl_b32 s9, s2, 10
	s_lshl_b64 s[2:3], s[42:43], 1
	v_lshlrev_b32_e32 v0, 4, v0
	s_add_i32 s7, s9, 0
	v_lshl_add_u64 v[4:5], v[8:9], 0, v[0:1]
	v_lshl_add_u64 v[8:9], v[2:3], 0, s[2:3]
	s_mov_b64 s[0:1], 0x400
	s_add_i32 s10, s7, 0x2000
	v_lshl_add_u64 v[10:11], v[8:9], 0, s[0:1]
	s_mov_b32 m0, s7
	s_mov_b64 s[18:19], 0x48400
	global_load_lds_dwordx4 v[10:11], off
	v_lshl_add_u64 v[8:9], v[8:9], 0, s[18:19]
	s_mov_b32 m0, s10
	s_add_i32 s88, s42, 0x48000
	s_add_i32 s11, s7, 0x4000
	global_load_lds_dwordx4 v[8:9], off
	v_lshl_add_u64 v[8:9], v[4:5], 0, s[2:3]
	s_mov_b64 s[2:3], 0x600
	s_add_i32 s13, s7, 0x6000
	s_lshl_b64 s[4:5], s[88:89], 1
	v_lshl_add_u64 v[10:11], v[8:9], 0, s[2:3]
	s_mov_b32 m0, s11
	s_mov_b64 s[10:11], 0x48600
	s_add_i32 s14, s7, 0x8000
	global_load_lds_dwordx4 v[10:11], off
	v_lshl_add_u64 v[8:9], v[8:9], 0, s[10:11]
	s_mov_b32 m0, s13
	v_lshl_add_u64 v[2:3], v[2:3], 0, s[4:5]
	s_add_i32 s15, s7, 0xa000
	global_load_lds_dwordx4 v[8:9], off
	v_lshl_add_u64 v[8:9], v[2:3], 0, s[0:1]
	s_mov_b32 m0, s14
	v_lshl_add_u64 v[2:3], v[2:3], 0, s[18:19]
	global_load_lds_dwordx4 v[8:9], off
	s_mov_b32 m0, s15
	s_add_i32 s75, s75, s94
	s_add_i32 s16, s7, 0xc000
	v_and_b32_e32 v124, 31, v17
	global_load_lds_dwordx4 v[2:3], off
	v_lshl_add_u64 v[2:3], v[4:5], 0, s[4:5]
	s_add_i32 s17, s7, 0xe000
	v_or_b32_e32 v14, s75, v124
	v_lshl_add_u64 v[4:5], v[2:3], 0, s[2:3]
	s_mov_b32 m0, s16
	v_lshl_add_u64 v[2:3], v[2:3], 0, s[10:11]
	global_load_lds_dwordx4 v[4:5], off
	s_mov_b32 m0, s17
	v_ashrrev_i32_e32 v15, 31, v14
	s_mov_b32 s0, s20
	global_load_lds_dwordx4 v[2:3], off
	v_writelane_b32 v254, s0, 9
	v_lshl_add_u64 v[2:3], v[14:15], 0, s[20:21]
	v_bfe_u32 v125, v17, 5, 1
	v_writelane_b32 v254, s1, 10
	v_mad_u64_u32 v[4:5], s[0:1], v2, s76, v[6:7]
	v_mad_i32_i24 v5, v3, s76, v5
	v_lshlrev_b32_e32 v2, 4, v125
	v_mov_b32_e32 v3, v1
	v_lshl_add_u64 v[18:19], v[4:5], 0, v[2:3]
	global_load_dwordx4 v[2:5], v[18:19], off offset:512
	global_load_dwordx4 v[6:9], v[18:19], off offset:544
	global_load_dwordx4 v[10:13], v[18:19], off offset:576
	s_nop 0
	global_load_dwordx4 v[18:21], v[18:19], off offset:608
	s_cmp_lt_u32 s46, 4
	v_mov_b32_e32 v15, s6
	s_cbranch_scc1 .LBB0_795
	v_readlane_b32 s0, v255, 38
	s_lshl_b32 s0, s0, 2
	v_readlane_b32 s1, v255, 27
	s_add_u32 s2, s1, s0
	v_readlane_b32 s0, v255, 28
	s_addc_u32 s3, s0, 0
	s_lshl_b32 s88, s45, 12
	s_lshl_b64 s[0:1], s[88:89], 2
	v_lshlrev_b32_e32 v15, 3, v125
	s_add_u32 s0, s2, s0
	s_addc_u32 s1, s3, s1
	v_lshlrev_b32_e32 v34, 2, v15
	global_load_dwordx4 v[22:25], v34, s[0:1] offset:16
	global_load_dwordx4 v[26:29], v34, s[0:1]
	global_load_dwordx4 v[30:33], v34, s[0:1] offset:1040
	global_load_dwordx4 v[40:43], v34, s[0:1] offset:1024
	s_waitcnt vmcnt(0)
	v_and_b32_e32 v71, 0xffff0000, v4
	v_and_b32_e32 v70, 0xffff0000, v2
	v_lshlrev_b32_e32 v65, 16, v4
	v_lshlrev_b32_e32 v64, 16, v2
	v_lshlrev_b32_e32 v67, 16, v5
	v_lshlrev_b32_e32 v66, 16, v3
	v_and_b32_e32 v63, 0xffff0000, v8
	v_and_b32_e32 v62, 0xffff0000, v6
	v_mov_b32_e32 v35, v1
	v_lshl_add_u64 v[38:39], s[0:1], 0, v[34:35]
	v_and_b32_e32 v69, 0xffff0000, v5
	v_and_b32_e32 v68, 0xffff0000, v3
	v_lshlrev_b32_e32 v57, 16, v8
	v_lshlrev_b32_e32 v56, 16, v6
	v_lshlrev_b32_e32 v59, 16, v9
	v_lshlrev_b32_e32 v58, 16, v7
	v_and_b32_e32 v61, 0xffff0000, v9
	v_and_b32_e32 v60, 0xffff0000, v7
	v_and_b32_e32 v55, 0xffff0000, v12
	v_and_b32_e32 v54, 0xffff0000, v10
	v_and_b32_e32 v53, 0xffff0000, v13
	v_and_b32_e32 v52, 0xffff0000, v11
	v_xor_b32_e32 v15, 32, v241
	v_cmp_lt_i32_e32 vcc, v15, v242
	s_cmp_eq_u32 s46, 4
	v_pk_add_f32 v[72:73], v[24:25], v[32:33]
	v_pk_add_f32 v[74:75], v[28:29], v[42:43]
	v_pk_add_f32 v[26:27], v[26:27], v[40:41]
	v_pk_add_f32 v[24:25], v[22:23], v[30:31]
	global_load_dwordx4 v[28:31], v34, s[0:1] offset:80
	global_load_dwordx4 v[40:43], v34, s[0:1] offset:64
	global_load_dwordx4 v[44:47], v34, s[0:1] offset:1104
	global_load_dwordx4 v[48:51], v34, s[0:1] offset:1088
	v_cndmask_b32_e32 v15, v241, v15, vcc
	v_lshlrev_b32_e32 v15, 2, v15
	s_waitcnt vmcnt(0)
	v_pk_add_f32 v[76:77], v[30:31], v[46:47]
	v_pk_add_f32 v[80:81], v[42:43], v[50:51]
	v_pk_add_f32 v[22:23], v[40:41], v[48:49]
	v_pk_add_f32 v[78:79], v[28:29], v[44:45]
	global_load_dwordx4 v[28:31], v34, s[0:1] offset:144
	global_load_dwordx4 v[40:43], v34, s[0:1] offset:128
	global_load_dwordx4 v[44:47], v34, s[0:1] offset:1168
	global_load_dwordx4 v[48:51], v34, s[0:1] offset:1152
	s_waitcnt vmcnt(0)
	v_pk_add_f32 v[82:83], v[30:31], v[46:47]
	v_pk_add_f32 v[86:87], v[42:43], v[50:51]
	v_pk_add_f32 v[88:89], v[40:41], v[48:49]
	v_pk_add_f32 v[84:85], v[28:29], v[44:45]
	global_load_dwordx4 v[28:31], v34, s[0:1] offset:208
	global_load_dwordx4 v[40:43], v34, s[0:1] offset:192
	global_load_dwordx4 v[44:47], v34, s[0:1] offset:1232
	global_load_dwordx4 v[90:93], v34, s[0:1] offset:1216
	v_lshlrev_b32_e32 v49, 16, v12
	v_lshlrev_b32_e32 v48, 16, v10
	v_lshlrev_b32_e32 v51, 16, v13
	v_lshlrev_b32_e32 v50, 16, v11
	s_waitcnt vmcnt(0)
	v_pk_add_f32 v[94:95], v[42:43], v[92:93]
	v_pk_add_f32 v[96:97], v[40:41], v[90:91]
	v_pk_add_f32 v[90:91], v[30:31], v[46:47]
	v_pk_add_f32 v[92:93], v[28:29], v[44:45]
	global_load_dwordx4 v[28:31], v34, s[0:1] offset:2064
	global_load_dwordx4 v[98:101], v34, s[0:1] offset:2048
	global_load_dwordx4 v[102:105], v34, s[0:1] offset:3088
	global_load_dwordx4 v[106:109], v34, s[0:1] offset:3072
	v_and_b32_e32 v47, 0xffff0000, v20
	v_and_b32_e32 v46, 0xffff0000, v18
	v_lshlrev_b32_e32 v45, 16, v20
	v_lshlrev_b32_e32 v44, 16, v18
	v_lshlrev_b32_e32 v43, 16, v21
	v_lshlrev_b32_e32 v42, 16, v19
	v_and_b32_e32 v41, 0xffff0000, v21
	v_and_b32_e32 v40, 0xffff0000, v19
	s_waitcnt vmcnt(0)
	v_pk_add_f32 v[28:29], v[28:29], v[102:103]
	v_pk_add_f32 v[36:37], v[98:99], v[106:107]
	v_pk_add_f32 v[98:99], v[30:31], v[104:105]
	v_mov_b32_e32 v31, v26
	v_mov_b32_e32 v26, v37
	v_pk_add_f32 v[32:33], v[100:101], v[108:109]
	v_mov_b32_e32 v30, v36
	v_pk_mul_f32 v[26:27], v[26:27], v[70:71] op_sel_hi:[1,0]
	v_mov_b32_e32 v104, v98
	v_pk_fma_f32 v[26:27], v[30:31], v[64:65], v[26:27] op_sel_hi:[1,0,1]
	v_mov_b32_e32 v30, v32
	v_mov_b32_e32 v31, v74
	v_pk_fma_f32 v[100:101], v[30:31], v[66:67], v[26:27] op_sel_hi:[1,0,1]
	v_mov_b32_e32 v27, v24
	v_mov_b32_e32 v24, v29
	v_mov_b32_e32 v30, v71
	v_mov_b32_e32 v26, v28
	v_mov_b32_e32 v28, v65
	v_pk_mul_f32 v[24:25], v[24:25], v[30:31] op_sel_hi:[1,0]
	v_mov_b32_e32 v74, v33
	v_pk_fma_f32 v[102:103], v[26:27], v[28:29], v[24:25] op_sel_hi:[1,0,1]
	global_load_dwordx4 v[24:27], v34, s[0:1] offset:2128
	global_load_dwordx4 v[28:31], v34, s[0:1] offset:2112
	global_load_dwordx4 v[112:115], v34, s[0:1] offset:3152
	global_load_dwordx4 v[106:109], v34, s[0:1] offset:3136
	v_mov_b32_e32 v105, v72
	v_mov_b32_e32 v72, v67
	s_waitcnt vmcnt(0)
	v_pk_add_f32 v[28:29], v[28:29], v[106:107]
	v_pk_add_f32 v[110:111], v[30:31], v[108:109]
	v_pk_add_f32 v[108:109], v[24:25], v[112:113]
	v_mov_b32_e32 v113, v22
	v_mov_b32_e32 v22, v29
	v_pk_add_f32 v[106:107], v[26:27], v[114:115]
	v_mov_b32_e32 v112, v28
	v_pk_mul_f32 v[114:115], v[22:23], v[62:63] op_sel_hi:[1,0]
	global_load_dwordx4 v[22:25], v34, s[0:1] offset:2192
	global_load_dwordx4 v[26:29], v34, s[0:1] offset:2176
	global_load_dwordx4 v[30:33], v34, s[0:1] offset:3216
	global_load_dwordx4 v[116:119], v34, s[0:1] offset:3200
	s_waitcnt vmcnt(0)
	v_pk_add_f32 v[120:121], v[28:29], v[118:119]
	v_pk_add_f32 v[122:123], v[26:27], v[116:117]
	v_pk_add_f32 v[116:117], v[24:25], v[32:33]
	v_pk_add_f32 v[118:119], v[22:23], v[30:31]
	global_load_dwordx4 v[22:25], v34, s[0:1] offset:2256
	global_load_dwordx4 v[30:33], v34, s[0:1] offset:2240
	global_load_dwordx4 v[26:29], v34, s[0:1] offset:3280
	s_nop 0
	global_load_dwordx4 v[34:37], v34, s[0:1] offset:3264
	s_mov_b64 s[0:1], 0x1000
	s_waitcnt vmcnt(0)
	v_pk_add_f32 v[24:25], v[24:25], v[28:29]
	v_pk_add_f32 v[30:31], v[30:31], v[34:35]
	v_pk_add_f32 v[22:23], v[22:23], v[26:27]
	v_pk_fma_f32 v[26:27], v[74:75], v[68:69], v[100:101] op_sel_hi:[1,0,1]
	v_pk_fma_f32 v[28:29], v[104:105], v[72:73], v[102:103] op_sel_hi:[1,0,1]
	v_mov_b32_e32 v72, v99
	v_mov_b32_e32 v34, v69
	v_pk_add_f32 v[26:27], v[26:27], 0 op_sel_hi:[1,0]
	v_pk_fma_f32 v[28:29], v[72:73], v[34:35], v[28:29] op_sel_hi:[1,0,1]
	v_mov_b32_e32 v34, v110
	v_pk_add_f32 v[26:27], v[26:27], v[28:29]
	v_pk_fma_f32 v[28:29], v[112:113], v[56:57], v[114:115] op_sel_hi:[1,0,1]
	v_mov_b32_e32 v35, v80
	v_pk_fma_f32 v[28:29], v[34:35], v[58:59], v[28:29] op_sel_hi:[1,0,1]
	v_mov_b32_e32 v80, v111
	v_pk_fma_f32 v[28:29], v[80:81], v[60:61], v[28:29] op_sel_hi:[1,0,1]
	v_pk_add_f32 v[32:33], v[32:33], v[36:37]
	v_pk_add_f32 v[26:27], v[26:27], v[28:29]
	v_mov_b32_e32 v29, v78
	v_mov_b32_e32 v78, v109
	v_mov_b32_e32 v36, v63
	v_mov_b32_e32 v28, v108
	v_mov_b32_e32 v34, v57
	v_pk_mul_f32 v[36:37], v[78:79], v[36:37] op_sel_hi:[1,0]
	s_nop 0
	v_pk_fma_f32 v[28:29], v[28:29], v[34:35], v[36:37] op_sel_hi:[1,0,1]
	v_mov_b32_e32 v34, v106
	v_mov_b32_e32 v35, v76
	v_mov_b32_e32 v36, v59
	v_pk_fma_f32 v[28:29], v[34:35], v[36:37], v[28:29] op_sel_hi:[1,0,1]
	v_mov_b32_e32 v76, v107
	v_mov_b32_e32 v34, v61
	v_pk_fma_f32 v[28:29], v[76:77], v[34:35], v[28:29] op_sel_hi:[1,0,1]
	v_mov_b32_e32 v36, v55
	v_pk_add_f32 v[26:27], v[26:27], v[28:29]
	v_mov_b32_e32 v29, v88
	v_mov_b32_e32 v88, v123
	v_mov_b32_e32 v28, v122
	v_pk_mul_f32 v[34:35], v[88:89], v[54:55] op_sel_hi:[1,0]
	s_nop 0
	v_pk_fma_f32 v[28:29], v[28:29], v[48:49], v[34:35] op_sel_hi:[1,0,1]
	v_mov_b32_e32 v34, v120
	v_mov_b32_e32 v35, v86
	v_pk_fma_f32 v[28:29], v[34:35], v[50:51], v[28:29] op_sel_hi:[1,0,1]
	v_mov_b32_e32 v86, v121
	v_pk_fma_f32 v[28:29], v[86:87], v[52:53], v[28:29] op_sel_hi:[1,0,1]
	v_mov_b32_e32 v34, v49
	v_pk_add_f32 v[26:27], v[26:27], v[28:29]
	v_mov_b32_e32 v29, v84
	v_mov_b32_e32 v84, v119
	v_mov_b32_e32 v28, v118
	v_pk_mul_f32 v[36:37], v[84:85], v[36:37] op_sel_hi:[1,0]
	s_nop 0
	v_pk_fma_f32 v[28:29], v[28:29], v[34:35], v[36:37] op_sel_hi:[1,0,1]
	v_mov_b32_e32 v34, v116
	v_mov_b32_e32 v35, v82
	v_mov_b32_e32 v36, v51
	v_pk_fma_f32 v[28:29], v[34:35], v[36:37], v[28:29] op_sel_hi:[1,0,1]
	v_mov_b32_e32 v82, v117
	v_mov_b32_e32 v34, v53
	v_pk_fma_f32 v[28:29], v[82:83], v[34:35], v[28:29] op_sel_hi:[1,0,1]
	s_nop 0
	v_pk_add_f32 v[26:27], v[26:27], v[28:29]
	v_mov_b32_e32 v29, v96
	v_mov_b32_e32 v96, v31
	v_mov_b32_e32 v28, v30
	v_pk_mul_f32 v[30:31], v[96:97], v[46:47] op_sel_hi:[1,0]
	s_nop 0
	v_pk_fma_f32 v[28:29], v[28:29], v[44:45], v[30:31] op_sel_hi:[1,0,1]
	v_mov_b32_e32 v30, v32
	v_mov_b32_e32 v31, v94
	v_pk_fma_f32 v[28:29], v[30:31], v[42:43], v[28:29] op_sel_hi:[1,0,1]
	v_mov_b32_e32 v94, v33
	v_pk_fma_f32 v[28:29], v[94:95], v[40:41], v[28:29] op_sel_hi:[1,0,1]
	v_mov_b32_e32 v30, v47
	v_pk_add_f32 v[26:27], v[26:27], v[28:29]
	v_mov_b32_e32 v29, v92
	v_mov_b32_e32 v92, v23
	v_mov_b32_e32 v28, v22
	v_mov_b32_e32 v22, v45
	v_pk_mul_f32 v[30:31], v[92:93], v[30:31] op_sel_hi:[1,0]
	s_nop 0
	v_pk_fma_f32 v[22:23], v[28:29], v[22:23], v[30:31] op_sel_hi:[1,0,1]
	v_mov_b32_e32 v28, v24
	v_mov_b32_e32 v29, v90
	v_mov_b32_e32 v24, v43
	v_pk_fma_f32 v[22:23], v[28:29], v[24:25], v[22:23] op_sel_hi:[1,0,1]
	v_mov_b32_e32 v90, v25
	v_mov_b32_e32 v24, v41
	v_pk_fma_f32 v[22:23], v[90:91], v[24:25], v[22:23] op_sel_hi:[1,0,1]
	v_lshl_add_u64 v[24:25], v[38:39], 0, s[0:1]
	s_mov_b64 s[0:1], 0x1400
	v_pk_add_f32 v[72:73], v[26:27], v[22:23]
	v_lshl_add_u64 v[22:23], v[38:39], 0, s[0:1]
	s_movk_i32 s0, 0x1000
	v_add_co_u32_e32 v30, vcc, s0, v38
	s_mov_b64 s[0:1], 0x1040
	s_nop 0
	v_addc_co_u32_e32 v31, vcc, 0, v39, vcc
	global_load_dwordx4 v[26:29], v[30:31], off
	global_load_dwordx4 v[32:35], v[24:25], off offset:16
	global_load_dwordx4 v[76:79], v[30:31], off offset:1024
	s_nop 0
	global_load_dwordx4 v[22:25], v[22:23], off offset:16
	ds_bpermute_b32 v75, v15, v73
	ds_bpermute_b32 v74, v15, v72
	s_waitcnt vmcnt(0)
	v_pk_add_f32 v[26:27], v[26:27], v[76:77]
	v_pk_add_f32 v[22:23], v[32:33], v[22:23]
	v_mul_f32_e32 v27, v27, v70
	v_pk_add_f32 v[28:29], v[28:29], v[78:79]
	v_fmac_f32_e32 v27, v26, v64
	v_mul_f32_e32 v23, v23, v71
	v_pk_add_f32 v[24:25], v[34:35], v[24:25]
	v_fmac_f32_e32 v27, v28, v66
	v_fmac_f32_e32 v23, v22, v65
	v_fmac_f32_e32 v27, v29, v68
	v_fmac_f32_e32 v23, v24, v67
	v_add_f32_e32 v26, 0, v27
	v_fmac_f32_e32 v23, v25, v69
	v_add_f32_e32 v80, v26, v23
	v_lshl_add_u64 v[26:27], v[38:39], 0, s[0:1]
	s_mov_b64 s[0:1], 0x1440
	global_load_dwordx4 v[22:25], v[30:31], off offset:64
	s_nop 0
	global_load_dwordx4 v[26:29], v[26:27], off offset:16
	v_lshl_add_u64 v[36:37], v[38:39], 0, s[0:1]
	global_load_dwordx4 v[32:35], v[30:31], off offset:1088
	global_load_dwordx4 v[76:79], v[36:37], off offset:16
	s_mov_b64 s[0:1], 0x1080
	s_waitcnt vmcnt(0)
	v_pk_add_f32 v[22:23], v[22:23], v[32:33]
	s_nop 0
	v_mul_f32_e32 v23, v23, v62
	v_pk_add_f32 v[24:25], v[24:25], v[34:35]
	v_fmac_f32_e32 v23, v22, v56
	v_fmac_f32_e32 v23, v24, v58
	v_pk_add_f32 v[26:27], v[26:27], v[76:77]
	v_fmac_f32_e32 v23, v25, v60
	v_add_f32_e32 v22, v80, v23
	v_mul_f32_e32 v23, v27, v63
	v_pk_add_f32 v[28:29], v[28:29], v[78:79]
	v_fmac_f32_e32 v23, v26, v57
	v_fmac_f32_e32 v23, v28, v59
	v_fmac_f32_e32 v23, v29, v61
	v_lshl_add_u64 v[26:27], v[38:39], 0, s[0:1]
	s_mov_b64 s[0:1], 0x1480
	v_add_f32_e32 v80, v22, v23
	global_load_dwordx4 v[22:25], v[30:31], off offset:128
	s_nop 0
	global_load_dwordx4 v[26:29], v[26:27], off offset:16
	v_lshl_add_u64 v[36:37], v[38:39], 0, s[0:1]
	global_load_dwordx4 v[32:35], v[30:31], off offset:1152
	global_load_dwordx4 v[76:79], v[36:37], off offset:16
	s_mov_b64 s[0:1], 0x10c0
	s_waitcnt vmcnt(0)
	v_pk_add_f32 v[22:23], v[22:23], v[32:33]
	s_nop 0
	v_mul_f32_e32 v23, v23, v54
	v_pk_add_f32 v[24:25], v[24:25], v[34:35]
	v_fmac_f32_e32 v23, v22, v48
	v_fmac_f32_e32 v23, v24, v50
	v_pk_add_f32 v[26:27], v[26:27], v[76:77]
	v_fmac_f32_e32 v23, v25, v52
	v_add_f32_e32 v22, v80, v23
	v_mul_f32_e32 v23, v27, v55
	v_pk_add_f32 v[28:29], v[28:29], v[78:79]
	v_fmac_f32_e32 v23, v26, v49
	v_fmac_f32_e32 v23, v28, v51
	v_fmac_f32_e32 v23, v29, v53
	v_lshl_add_u64 v[26:27], v[38:39], 0, s[0:1]
	s_mov_b64 s[0:1], 0x14c0
	v_add_f32_e32 v80, v22, v23
	global_load_dwordx4 v[22:25], v[30:31], off offset:192
	s_nop 0
	global_load_dwordx4 v[26:29], v[26:27], off offset:16
	v_lshl_add_u64 v[36:37], v[38:39], 0, s[0:1]
	global_load_dwordx4 v[32:35], v[30:31], off offset:1216
	global_load_dwordx4 v[76:79], v[36:37], off offset:16
	s_mov_b64 s[0:1], 0x1800
	s_waitcnt vmcnt(0)
	v_pk_add_f32 v[22:23], v[22:23], v[32:33]
	s_nop 0
	v_mul_f32_e32 v23, v23, v46
	v_pk_add_f32 v[24:25], v[24:25], v[34:35]
	v_fmac_f32_e32 v23, v22, v44
	v_fmac_f32_e32 v23, v24, v42
	v_pk_add_f32 v[26:27], v[26:27], v[76:77]
	v_fmac_f32_e32 v23, v25, v40
	v_add_f32_e32 v22, v80, v23
	v_mul_f32_e32 v23, v27, v47
	v_pk_add_f32 v[28:29], v[28:29], v[78:79]
	v_fmac_f32_e32 v23, v26, v45
	v_fmac_f32_e32 v23, v28, v43
	v_fmac_f32_e32 v23, v29, v41
	v_lshl_add_u64 v[26:27], v[38:39], 0, s[0:1]
	s_mov_b64 s[0:1], 0x1c00
	v_add_f32_e32 v76, v22, v23
	v_lshl_add_u64 v[36:37], v[38:39], 0, s[0:1]
	global_load_dwordx4 v[22:25], v[30:31], off offset:2048
	s_nop 0
	global_load_dwordx4 v[26:29], v[26:27], off offset:16
	s_nop 0
	global_load_dwordx4 v[32:35], v[30:31], off offset:3072
	global_load_dwordx4 v[78:81], v[36:37], off offset:16
	s_mov_b64 s[0:1], 0x1840
	ds_bpermute_b32 v77, v15, v76
	s_waitcnt vmcnt(0)
	v_pk_add_f32 v[22:23], v[22:23], v[32:33]
	s_nop 0
	v_mul_f32_e32 v23, v23, v70
	v_pk_add_f32 v[24:25], v[24:25], v[34:35]
	v_fmac_f32_e32 v23, v22, v64
	v_fmac_f32_e32 v23, v24, v66
	v_pk_add_f32 v[26:27], v[26:27], v[78:79]
	v_fmac_f32_e32 v23, v25, v68
	v_add_f32_e32 v22, 0, v23
	v_mul_f32_e32 v23, v27, v71
	v_pk_add_f32 v[28:29], v[28:29], v[80:81]
	v_fmac_f32_e32 v23, v26, v65
	v_fmac_f32_e32 v23, v28, v67
	v_fmac_f32_e32 v23, v29, v69
	v_lshl_add_u64 v[26:27], v[38:39], 0, s[0:1]
	s_mov_b64 s[0:1], 0x1c40
	v_add_f32_e32 v82, v22, v23
	global_load_dwordx4 v[22:25], v[30:31], off offset:2112
	s_nop 0
	global_load_dwordx4 v[26:29], v[26:27], off offset:16
	v_lshl_add_u64 v[36:37], v[38:39], 0, s[0:1]
	global_load_dwordx4 v[32:35], v[30:31], off offset:3136
	global_load_dwordx4 v[78:81], v[36:37], off offset:16
	s_mov_b64 s[0:1], 0x1880
	s_waitcnt vmcnt(0)
	v_pk_add_f32 v[22:23], v[22:23], v[32:33]
	s_nop 0
	v_mul_f32_e32 v23, v23, v62
	v_pk_add_f32 v[24:25], v[24:25], v[34:35]
	v_fmac_f32_e32 v23, v22, v56
	v_fmac_f32_e32 v23, v24, v58
	v_pk_add_f32 v[26:27], v[26:27], v[78:79]
	v_fmac_f32_e32 v23, v25, v60
	v_add_f32_e32 v22, v82, v23
	v_mul_f32_e32 v23, v27, v63
	v_pk_add_f32 v[28:29], v[28:29], v[80:81]
	v_fmac_f32_e32 v23, v26, v57
	v_fmac_f32_e32 v23, v28, v59
	v_fmac_f32_e32 v23, v29, v61
	v_lshl_add_u64 v[26:27], v[38:39], 0, s[0:1]
	s_mov_b64 s[0:1], 0x1c80
	v_add_f32_e32 v82, v22, v23
	global_load_dwordx4 v[22:25], v[30:31], off offset:2176
	s_nop 0
	global_load_dwordx4 v[26:29], v[26:27], off offset:16
	v_lshl_add_u64 v[36:37], v[38:39], 0, s[0:1]
	global_load_dwordx4 v[32:35], v[30:31], off offset:3200
	global_load_dwordx4 v[78:81], v[36:37], off offset:16
	s_mov_b64 s[0:1], 0x18c0
	s_waitcnt vmcnt(0)
	v_pk_add_f32 v[22:23], v[22:23], v[32:33]
	s_nop 0
	v_mul_f32_e32 v23, v23, v54
	v_pk_add_f32 v[24:25], v[24:25], v[34:35]
	v_fmac_f32_e32 v23, v22, v48
	v_fmac_f32_e32 v23, v24, v50
	v_pk_add_f32 v[26:27], v[26:27], v[78:79]
	v_fmac_f32_e32 v23, v25, v52
	v_add_f32_e32 v22, v82, v23
	v_mul_f32_e32 v23, v27, v55
	v_pk_add_f32 v[28:29], v[28:29], v[80:81]
	v_fmac_f32_e32 v23, v26, v49
	v_fmac_f32_e32 v23, v28, v51
	v_fmac_f32_e32 v23, v29, v53
	v_add_f32_e32 v78, v22, v23
	v_lshl_add_u64 v[22:23], v[38:39], 0, s[0:1]
	s_mov_b64 s[0:1], 0x1cc0
	v_lshl_add_u64 v[32:33], v[38:39], 0, s[0:1]
	global_load_dwordx4 v[26:29], v[30:31], off offset:2240
	s_nop 0
	global_load_dwordx4 v[22:25], v[22:23], off offset:16
	s_nop 0
	global_load_dwordx4 v[34:37], v[30:31], off offset:3264
	s_nop 0
	global_load_dwordx4 v[30:33], v[32:33], off offset:16
	s_waitcnt vmcnt(0)
	v_pk_add_f32 v[26:27], v[26:27], v[34:35]
	v_pk_add_f32 v[22:23], v[22:23], v[30:31]
	v_mul_f32_e32 v27, v27, v46
	v_pk_add_f32 v[28:29], v[28:29], v[36:37]
	v_fmac_f32_e32 v27, v26, v44
	v_mul_f32_e32 v23, v23, v47
	v_pk_add_f32 v[24:25], v[24:25], v[32:33]
	v_fmac_f32_e32 v27, v28, v42
	v_fmac_f32_e32 v23, v22, v45
	v_fmac_f32_e32 v27, v29, v40
	v_fmac_f32_e32 v23, v24, v43
	v_add_f32_e32 v26, v78, v27
	v_fmac_f32_e32 v23, v25, v41
	v_add_f32_e32 v24, v26, v23
	ds_bpermute_b32 v25, v15, v24
	v_mov_b32_e32 v27, 0xff800000
	v_mov_b32_e32 v26, 0xff800000
	s_cbranch_scc1 .LBB0_846
	s_mov_b64 s[0:1], 0x2000
	v_add_co_u32_e32 v22, vcc, 0x2000, v38
	v_lshl_add_u64 v[32:33], v[38:39], 0, s[0:1]
	s_mov_b64 s[0:1], 0x2400
	v_addc_co_u32_e32 v23, vcc, 0, v39, vcc
	v_lshl_add_u64 v[36:37], v[38:39], 0, s[0:1]
	global_load_dwordx4 v[28:31], v[22:23], off
	s_nop 0
	global_load_dwordx4 v[32:35], v[32:33], off offset:16
	s_nop 0
	global_load_dwordx4 v[78:81], v[22:23], off offset:1024
	global_load_dwordx4 v[82:85], v[36:37], off offset:16
	s_mov_b64 s[0:1], 0x2040
	s_waitcnt vmcnt(0)
	v_pk_add_f32 v[28:29], v[28:29], v[78:79]
	v_pk_add_f32 v[32:33], v[32:33], v[82:83]
	v_pk_add_f32 v[30:31], v[30:31], v[80:81]
	v_mov_b32_e32 v37, v32
	v_mov_b32_e32 v32, v29
	v_pk_add_f32 v[34:35], v[34:35], v[84:85]
	v_mov_b32_e32 v36, v28
	v_pk_mul_f32 v[28:29], v[32:33], v[70:71]
	v_mov_b32_e32 v32, v30
	v_pk_fma_f32 v[28:29], v[36:37], v[64:65], v[28:29]
	v_mov_b32_e32 v33, v34
	v_pk_fma_f32 v[28:29], v[32:33], v[66:67], v[28:29]
	v_mov_b32_e32 v34, v31
	v_pk_fma_f32 v[28:29], v[34:35], v[68:69], v[28:29]
	v_lshl_add_u64 v[32:33], v[38:39], 0, s[0:1]
	v_add_f32_e32 v26, 0, v28
	s_mov_b64 s[0:1], 0x2440
	v_add_f32_e32 v26, v26, v29
	global_load_dwordx4 v[28:31], v[22:23], off offset:64
	s_nop 0
	global_load_dwordx4 v[32:35], v[32:33], off offset:16
	v_lshl_add_u64 v[36:37], v[38:39], 0, s[0:1]
	global_load_dwordx4 v[78:81], v[22:23], off offset:1088
	global_load_dwordx4 v[82:85], v[36:37], off offset:16
	s_mov_b64 s[0:1], 0x2080
	s_waitcnt vmcnt(0)
	v_pk_add_f32 v[28:29], v[28:29], v[78:79]
	v_pk_add_f32 v[32:33], v[32:33], v[82:83]
	v_pk_add_f32 v[30:31], v[30:31], v[80:81]
	v_mov_b32_e32 v37, v32
	v_mov_b32_e32 v32, v29
	v_pk_add_f32 v[34:35], v[34:35], v[84:85]
	v_mov_b32_e32 v36, v28
	v_pk_mul_f32 v[28:29], v[32:33], v[62:63]
	v_mov_b32_e32 v32, v30
	v_pk_fma_f32 v[28:29], v[36:37], v[56:57], v[28:29]
	v_mov_b32_e32 v33, v34
	v_pk_fma_f32 v[28:29], v[32:33], v[58:59], v[28:29]
	v_mov_b32_e32 v34, v31
	v_pk_fma_f32 v[28:29], v[34:35], v[60:61], v[28:29]
	v_lshl_add_u64 v[32:33], v[38:39], 0, s[0:1]
	v_add_f32_e32 v26, v26, v28
	s_mov_b64 s[0:1], 0x2480
	v_add_f32_e32 v26, v26, v29
	global_load_dwordx4 v[28:31], v[22:23], off offset:128
	s_nop 0
	global_load_dwordx4 v[32:35], v[32:33], off offset:16
	v_lshl_add_u64 v[36:37], v[38:39], 0, s[0:1]
	global_load_dwordx4 v[78:81], v[22:23], off offset:1152
	global_load_dwordx4 v[82:85], v[36:37], off offset:16
	s_mov_b64 s[0:1], 0x20c0
	s_waitcnt vmcnt(0)
	v_pk_add_f32 v[28:29], v[28:29], v[78:79]
	v_pk_add_f32 v[32:33], v[32:33], v[82:83]
	v_pk_add_f32 v[30:31], v[30:31], v[80:81]
	v_mov_b32_e32 v37, v32
	v_mov_b32_e32 v32, v29
	v_pk_add_f32 v[34:35], v[34:35], v[84:85]
	v_mov_b32_e32 v36, v28
	v_pk_mul_f32 v[28:29], v[32:33], v[54:55]
	v_mov_b32_e32 v32, v30
	v_pk_fma_f32 v[28:29], v[36:37], v[48:49], v[28:29]
	v_mov_b32_e32 v33, v34
	v_pk_fma_f32 v[28:29], v[32:33], v[50:51], v[28:29]
	v_mov_b32_e32 v34, v31
	v_pk_fma_f32 v[28:29], v[34:35], v[52:53], v[28:29]
	v_lshl_add_u64 v[32:33], v[38:39], 0, s[0:1]
	v_add_f32_e32 v26, v26, v28
	s_mov_b64 s[0:1], 0x24c0
	v_add_f32_e32 v26, v26, v29
	global_load_dwordx4 v[28:31], v[22:23], off offset:192
	s_nop 0
	global_load_dwordx4 v[32:35], v[32:33], off offset:16
	v_lshl_add_u64 v[36:37], v[38:39], 0, s[0:1]
	global_load_dwordx4 v[78:81], v[22:23], off offset:1216
	global_load_dwordx4 v[82:85], v[36:37], off offset:16
	s_waitcnt vmcnt(0)
	v_pk_add_f32 v[28:29], v[28:29], v[78:79]
	v_pk_add_f32 v[32:33], v[32:33], v[82:83]
	v_pk_add_f32 v[22:23], v[30:31], v[80:81]
	v_pk_add_f32 v[30:31], v[34:35], v[84:85]
	v_mov_b32_e32 v35, v32
	v_mov_b32_e32 v32, v29
	v_mov_b32_e32 v34, v28
	v_pk_mul_f32 v[28:29], v[32:33], v[46:47]
	v_mov_b32_e32 v32, v22
	v_pk_fma_f32 v[28:29], v[34:35], v[44:45], v[28:29]
	v_mov_b32_e32 v33, v30
	v_pk_fma_f32 v[28:29], v[32:33], v[42:43], v[28:29]
	v_mov_b32_e32 v30, v23
	v_pk_fma_f32 v[22:23], v[30:31], v[40:41], v[28:29]
	s_nop 0
	v_add_f32_e32 v22, v26, v22
	v_add_f32_e32 v22, v22, v23
	ds_bpermute_b32 v23, v15, v22
	s_waitcnt lgkmcnt(0)
	v_add_f32_e32 v26, v22, v23
	s_cmp_lt_u32 s46, 6
	s_cbranch_scc0 .LBB0_847

.LBB0_795:
	v_lshlrev_b32_e32 v22, 6, v127
	v_and_b32_e32 v32, 64, v22
	v_lshlrev_b32_e32 v22, 1, v17
	v_and_b32_e32 v33, 32, v22
	v_lshlrev_b32_e32 v22, 3, v17
	s_add_i32 s77, s9, 0x16000
	s_add_i32 s81, s9, 0x14000
	s_add_i32 s2, s9, 0x12000
	s_add_i32 s3, s9, 0x10000
	v_add_u32_e32 v24, s8, v127
	s_and_b32 s4, s44, 3
	v_readlane_b32 s8, v254, 0
	s_lshl_b32 s91, s46, 2
	v_and_b32_e32 v34, 24, v22
	v_lshrrev_b32_e32 v22, 1, v17
	s_or_b32 s13, s75, 31
	s_lshl_b32 s4, s4, 7
	v_readlane_b32 s10, v254, 2
	v_bfe_u32 v23, v17, 1, 3
	v_bitop3_b32 v22, v125, v22, 7 bitop3:0x78
	v_readlane_b32 s11, v254, 3
	s_add_u32 s4, s10, s4
	v_lshlrev_b32_e32 v27, 4, v22
	v_bitop3_b32 v22, v125, v23, 2 bitop3:0x36
	s_mul_i32 s0, s45, 0x900000
	s_addc_u32 s5, s11, 0
	v_lshlrev_b32_e32 v28, 4, v22
	v_bitop3_b32 v22, v125, v23, 4 bitop3:0x36
	s_mul_hi_u32 s1, s45, 0x900000
	s_add_u32 s0, s4, s0
	v_lshlrev_b32_e32 v29, 4, v22
	v_bitop3_b32 v22, v125, v23, 6 bitop3:0x36
	s_addc_u32 s1, s5, s1
	v_readlane_b32 s100, v255, 43
	s_add_u32 s0, s0, s100
	s_addc_u32 s1, s1, 0
	v_lshlrev_b32_e32 v30, 4, v22
	v_mov_b64_e32 v[22:23], s[0:1]
	v_mad_i64_i32 v[22:23], s[0:1], v24, s76, v[22:23]
	v_or3_b32 v35, v33, v34, 64
	s_add_i32 s0, 0, 0x4000
	v_lshlrev_b32_e32 v17, 5, v17
	v_xad_u32 v35, v35, v32, s0
	v_lshlrev_b32_e32 v36, 9, v125
	v_and_b32_e32 v37, 0x180, v17
	v_add3_u32 v17, v35, v36, v37
	v_add_u32_e32 v35, s0, v36
	v_add3_u32 v32, v35, v37, v32
	v_mov_b32_e32 v48, v1
	v_mov_b32_e32 v49, v1
	v_writelane_b32 v255, s88, 39
	v_and_b32_e32 v24, 7, v126
	s_lshl_b32 s86, s46, 16
	v_add3_u32 v128, v32, v33, v34
	v_mov_b32_e32 v50, v1
	v_mov_b32_e32 v51, v1
	v_mov_b32_e32 v52, v1
	v_mov_b32_e32 v53, v1
	v_mov_b32_e32 v54, v1
	v_mov_b32_e32 v55, v1
	v_mov_b32_e32 v56, v1
	v_mov_b32_e32 v57, v1
	v_mov_b32_e32 v58, v1
	v_mov_b32_e32 v59, v1
	v_mov_b32_e32 v60, v1
	v_mov_b32_e32 v61, v1
	v_mov_b32_e32 v62, v1
	v_mov_b32_e32 v63, v1
	v_mov_b64_e32 v[32:33], v[48:49]
	v_writelane_b32 v255, s89, 40
	s_mov_b32 s80, 2
	v_lshlrev_b32_e32 v26, 2, v125
	v_subrev_u32_e32 v31, 64, v14
	v_lshlrev_b32_e32 v24, 4, v24
	v_mov_b32_e32 v25, v1
	s_add_i32 s86, s86, 0x10000
	s_add_i32 s87, s91, 4
	v_lshl_add_u32 v129, v124, 7, 0
	s_mov_b32 s74, 0
	v_mov_b32_e32 v130, 0
	v_mov_b32_e32 v131, 0xff800000
	s_mov_b32 s90, -4
	v_mov_b64_e32 v[34:35], v[50:51]
	v_mov_b64_e32 v[36:37], v[52:53]
	v_mov_b64_e32 v[38:39], v[54:55]
	v_mov_b64_e32 v[40:41], v[56:57]
	v_mov_b64_e32 v[42:43], v[58:59]
	v_mov_b64_e32 v[44:45], v[60:61]
	v_mov_b64_e32 v[46:47], v[62:63]
	s_mov_b32 s88, 0
	s_waitcnt vmcnt(0) lgkmcnt(0)
	s_barrier
	v_readlane_b32 s9, v254, 1
	s_branch .LBB0_798

	.amdhsa_kernel _Z14fwd_megakernel4Args
		.amdhsa_group_segment_fixed_size 0
		.amdhsa_private_segment_fixed_size 0
		.amdhsa_kernarg_size 440
		.amdhsa_user_sgpr_count 2
		.amdhsa_user_sgpr_dispatch_ptr 0
		.amdhsa_user_sgpr_queue_ptr 0
		.amdhsa_user_sgpr_kernarg_segment_ptr 1
		.amdhsa_user_sgpr_dispatch_id 0
		.amdhsa_user_sgpr_kernarg_preload_length 0
		.amdhsa_user_sgpr_kernarg_preload_offset 0
		.amdhsa_user_sgpr_private_segment_size 0
		.amdhsa_uses_dynamic_stack 0
		.amdhsa_enable_private_segment 0
		.amdhsa_system_sgpr_workgroup_id_x 1
		.amdhsa_system_sgpr_workgroup_id_y 0
		.amdhsa_system_sgpr_workgroup_id_z 0
		.amdhsa_system_sgpr_workgroup_info 0
		.amdhsa_system_vgpr_workitem_id 2
		.amdhsa_next_free_vgpr 256
		.amdhsa_next_free_sgpr 102
		.amdhsa_accum_offset 256
		.amdhsa_reserve_vcc 1
		.amdhsa_float_round_mode_32 0
		.amdhsa_float_round_mode_16_64 0
		.amdhsa_float_denorm_mode_32 3
		.amdhsa_float_denorm_mode_16_64 3
		.amdhsa_dx10_clamp 1
		.amdhsa_ieee_mode 1
		.amdhsa_fp16_overflow 0
		.amdhsa_tg_split 0
		.amdhsa_exception_fp_ieee_invalid_op 0
		.amdhsa_exception_fp_denorm_src 0
		.amdhsa_exception_fp_ieee_div_zero 0
		.amdhsa_exception_fp_ieee_overflow 0
		.amdhsa_exception_fp_ieee_underflow 0
		.amdhsa_exception_fp_ieee_inexact 0
		.amdhsa_exception_int_div_zero 0
	.end_amdhsa_kernel

amdhsa.kernels:
  - .agpr_count:     0
    .args:
      - .offset:         0
        .size:           184
        .value_kind:     by_value
      - .offset:         184
        .size:           4
        .value_kind:     hidden_block_count_x
      - .offset:         188
        .size:           4
        .value_kind:     hidden_block_count_y
      - .offset:         192
        .size:           4
        .value_kind:     hidden_block_count_z
      - .offset:         196
        .size:           2
        .value_kind:     hidden_group_size_x
      - .offset:         198
        .size:           2
        .value_kind:     hidden_group_size_y
      - .offset:         200
        .size:           2
        .value_kind:     hidden_group_size_z
      - .offset:         202
        .size:           2
        .value_kind:     hidden_remainder_x
      - .offset:         204
        .size:           2
        .value_kind:     hidden_remainder_y
      - .offset:         206
        .size:           2
        .value_kind:     hidden_remainder_z
      - .offset:         224
        .size:           8
        .value_kind:     hidden_global_offset_x
      - .offset:         232
        .size:           8
        .value_kind:     hidden_global_offset_y
      - .offset:         240
        .size:           8
        .value_kind:     hidden_global_offset_z
      - .offset:         248
        .size:           2
        .value_kind:     hidden_grid_dims
      - .offset:         272
        .size:           8
        .value_kind:     hidden_multigrid_sync_arg
      - .offset:         304
        .size:           4
        .value_kind:     hidden_dynamic_lds_size
    .group_segment_fixed_size: 0
    .kernarg_segment_align: 8
    .kernarg_segment_size: 440
    .language:       OpenCL C
    .language_version:
      - 2
      - 0
    .max_flat_workgroup_size: 512
    .name:           _Z14fwd_megakernel4Args
    .private_segment_fixed_size: 0
    .sgpr_count:     108
    .sgpr_spill_count: 111
    .symbol:         _Z14fwd_megakernel4Args.kd
    .uniform_work_group_size: 1
    .uses_dynamic_stack: false
    .vgpr_count:     256
    .vgpr_spill_count: 0
    .wavefront_size: 64
